# ffn1 w2 copy moved from P0 to P1's idle workgroups; Wa/Wb/Wo copies behind the sample sequences in P4b
# speedup vs baseline: 1.0081x; 1.0018x over previous
; #define GAS __attribute__((address_space(1)))
; #define LAS __attribute__((address_space(3)))
; #define LDS_WAIT() asm volatile("s_waitcnt lgkmcnt(0)" ::: "memory")
; __device__ __forceinline__ unsigned pk2(float lo, float hi) { const f32x2_t_ v = {lo, hi}; return __builtin_bit_cast(unsigned, __builtin_convertvector(v, bf16x2_t_)); }
; __device__ __forceinline__ const float* kin(int k) { KArgs p = (KArgs)__builtin_amdgcn_kernarg_segment_ptr(); asm volatile("" : "+s"(p)); return p->in[k]; }
; __device__ __forceinline__ void transpose_item(const float* W, const float* g, int ldw, int K, int ncols, bf16* WT, int mode, int roff, LAS float* scr, int item, int lane) {
;     const int nblk = ncols / 32, kb = item / nblk, nb = item % nblk, k0 = 64 * kb, n0 = 32 * nb;
;     const float g0 = g ? g[k0 + lane] : 1.0f;
; #pragma unroll 8
;     for (int i = 0; i < 32; ++i) { const int kk = 2 * i + (lane >> 5); scr[kk * 33 + (lane & 31)] = W[(size_t)(k0 + kk) * ldw + n0 + (lane & 31)] * __shfl(g0, kk); }
;     LDS_WAIT(); asm volatile("" ::: "memory");
;     const int c = lane & 7;
; #pragma unroll
;     for (int j = 0; j < 4; ++j) { const int n = (lane >> 3) + 8 * j; const LAS float* s = scr + (8 * c) * 33 + n;
;         v4u o; o.x = pk2(s[0 * 33], s[1 * 33]); o.y = pk2(s[2 * 33], s[3 * 33]); o.z = pk2(s[4 * 33], s[5 * 33]); o.w = pk2(s[6 * 33], s[7 * 33]);
;         const int jc = n0 + n; const int drow = mode ? roff + ((jc >> 4) << 5) + (jc & 15) : roff + jc;
;         *(GAS v4u*)(WT + (size_t)drow * K + k0 + 8 * c) = o; }
;     LDS_WAIT(); asm volatile("" ::: "memory");
; }
; __global__ void __launch_bounds__(NWAVES * 64, 2) mk_fwd(Args args) {
;     ...
;         conv_w13(kin(6), kin(7), nullptr, ws, SCR_, F.lane, GW_, NGW);
;         conv_w2(kin(8), ws, SCR_, F.lane, (GW_ + NGW / 4) % NGW, NGW);
;         { const float* win = kin(10); bf16* WIN = (bf16*)(ws + WS_WIN);
;           conv_mat(win, nullptr, NIN, DM, 2560, WIN, 0, 0, SCR_, F.lane, (GW_ + NGW / 2) % NGW, NGW);
;           conv_mat(win + 2560, nullptr, NIN, DM, 512, WIN, 1, 2560, SCR_, F.lane, (GW_ + NGW / 8) % NGW, NGW);
;           conv_mat(win + 3072, nullptr, NIN, DM, 512, WIN, 1, 2560 + 16, SCR_, F.lane, (GW_ + 3 * (NGW / 8)) % NGW, NGW);
;           conv_mat(win + 3584, nullptr, NIN, DM, 2048, WIN, 0, 3584, SCR_, F.lane, (GW_ + 3 * (NGW / 4)) % NGW, NGW); }
.LBB0_13:
	s_or_b64 exec, exec, s[6:7]
	s_lshr_b32 s50, s3, 6
	s_add_u32 s30, s22, 0x2080000
	s_addc_u32 s31, s23, 0
	s_lshl_b32 s76, s18, 3
	s_bitcmp0_b32 s74, 0
	v_and_b32_e32 v189, 63, v0
	s_cbranch_scc1 .LBB0_63
	s_mov_b64 exec, -1
	v_readfirstlane_b32 s3, v0
	s_lshr_b32 s3, s3, 6
	s_lshl_b32 s12, s3, 14
	s_lshl_b32 s10, s33, 3
	s_add_i32 s10, s10, s3
	s_lshl_b32 s11, s18, 3
	v_and_b32_e32 v15, 63, v0
	v_lshrrev_b32_e32 v2, 3, v15
	v_and_b32_e32 v3, 7, v15
	v_lshlrev_b32_e32 v3, 4, v3
	v_mul_u32_u24_e32 v4, 0x84, v2
	v_add3_u32 v4, v4, v3, s12
	v_and_b32_e32 v5, 7, v15
	v_mul_u32_u24_e32 v5, 0x420, v5
	v_lshl_add_u32 v5, v2, 2, v5
	v_add_u32_e32 v5, s12, v5
	v_add_u32_e32 v6, 0, v2
	v_lshrrev_b32_e32 v10, 4, v6
	v_lshlrev_b32_e32 v10, 5, v10
	v_and_b32_e32 v14, 15, v6
	v_or_b32_e32 v10, v10, v14
	v_add_u32_e32 v7, 8, v2
	v_lshrrev_b32_e32 v11, 4, v7
	v_lshlrev_b32_e32 v11, 5, v11
	v_and_b32_e32 v14, 15, v7
	v_or_b32_e32 v11, v11, v14
	v_add_u32_e32 v8, 16, v2
	v_lshrrev_b32_e32 v12, 4, v8
	v_lshlrev_b32_e32 v12, 5, v12
	v_and_b32_e32 v14, 15, v8
	v_or_b32_e32 v12, v12, v14
	v_add_u32_e32 v9, 24, v2
	v_lshrrev_b32_e32 v13, 4, v9
	v_lshlrev_b32_e32 v13, 5, v13
	v_and_b32_e32 v14, 15, v9
	v_or_b32_e32 v13, v13, v14
	s_cmp_lt_u32 s10, 5632
	s_cbranch_scc0 .Lcw_p0_done
	s_cmp_lt_u32 s10, 1408
	s_cbranch_scc1 .Lcw_p0_i0_c0
	s_cmp_lt_u32 s10, 2816
	s_cbranch_scc1 .Lcw_p0_i0_c1
	s_cmp_lt_u32 s10, 4096
	s_cbranch_scc1 .Lcw_p0_i0_c2
	s_cmp_lt_u32 s10, 4352
	s_cbranch_scc1 .Lcw_p0_i0_c3
	s_cmp_lt_u32 s10, 4608
	s_cbranch_scc1 .Lcw_p0_i0_c4
.Lcw_p0_i0_c5:
	s_load_dwordx2 s[8:9], s[0:1], 0x50
	s_sub_u32 s14, s10, 4608
	s_lshr_b32 s15, s14, 6
	s_and_b32 s16, s14, 63
	s_mul_i32 s17, s15, 0x160000
	s_lshl_b32 s19, s16, 7
	s_add_u32 s17, s17, s19
	s_add_u32 s17, s17, 0x3800
	s_mov_b32 s3, 0x5800
	s_mul_i32 s46, s16, 0x10000
	s_lshl_b32 s47, s15, 7
	s_add_u32 s46, s46, s47
	s_add_u32 s46, s46, 0x800000
	s_add_u32 s34, s22, s46
	s_addc_u32 s35, s23, 0
	s_mov_b32 s36, 0x800
	s_mov_b64 s[38:39], 0
	s_branch .Lcw_p0_i0_go
.Lcw_p0_i0_c4:
	s_load_dwordx2 s[8:9], s[0:1], 0x50
	s_sub_u32 s14, s10, 4352
	s_lshr_b32 s15, s14, 4
	s_and_b32 s16, s14, 15
	s_mul_i32 s17, s15, 0x160000
	s_lshl_b32 s19, s16, 7
	s_add_u32 s17, s17, s19
	s_add_u32 s17, s17, 0x3000
	s_mov_b32 s3, 0x5800
	s_mul_i32 s46, s16, 0x20000
	s_lshl_b32 s47, s15, 7
	s_add_u32 s46, s46, s47
	s_add_u32 s46, s46, 0x608000
	s_add_u32 s34, s22, s46
	s_addc_u32 s35, s23, 0
	s_mov_b32 s36, 0x800
	s_mov_b64 s[38:39], -1
	s_branch .Lcw_p0_i0_go
.Lcw_p0_i0_c3:
	s_load_dwordx2 s[8:9], s[0:1], 0x50
	s_sub_u32 s14, s10, 4096
	s_lshr_b32 s15, s14, 4
	s_and_b32 s16, s14, 15
	s_mul_i32 s17, s15, 0x160000
	s_lshl_b32 s19, s16, 7
	s_add_u32 s17, s17, s19
	s_add_u32 s17, s17, 0x2800
	s_mov_b32 s3, 0x5800
	s_mul_i32 s46, s16, 0x20000
	s_lshl_b32 s47, s15, 7
	s_add_u32 s46, s46, s47
	s_add_u32 s46, s46, 0x600000
	s_add_u32 s34, s22, s46
	s_addc_u32 s35, s23, 0
	s_mov_b32 s36, 0x800
	s_mov_b64 s[38:39], -1
	s_branch .Lcw_p0_i0_go
.Lcw_p0_i0_c2:
	s_load_dwordx2 s[8:9], s[0:1], 0x50
	s_sub_u32 s14, s10, 2816
	s_mul_hi_u32 s15, s14, 0x3333334
	s_mul_i32 s16, s15, 80
	s_sub_u32 s16, s14, s16
	s_mul_i32 s17, s15, 0x160000
	s_lshl_b32 s19, s16, 7
	s_add_u32 s17, s17, s19
	s_mov_b32 s3, 0x5800
	s_mul_i32 s46, s16, 0x10000
	s_lshl_b32 s47, s15, 7
	s_add_u32 s46, s46, s47
	s_add_u32 s46, s46, 0x100000
	s_add_u32 s34, s22, s46
	s_addc_u32 s35, s23, 0
	s_mov_b32 s36, 0x800
	s_mov_b64 s[38:39], 0
	s_branch .Lcw_p0_i0_go

; #define LAS __attribute__((address_space(3)))
; __device__ __forceinline__ const float* kin(int k) { KArgs p = (KArgs)__builtin_amdgcn_kernarg_segment_ptr(); asm volatile("" : "+s"(p)); return p->in[k]; }
; __device__ __forceinline__ void conv_mat(const float* W, const float* g, int ldw, int K, int ncols, bf16* WT, int mode, int roff, LAS float* scr, int lane, int gw, int NGW) {
;     const int nitems = (K / 64) * (ncols / 32);
;     for (int it = gw; it < nitems; it += NGW) transpose_item(W, g, ldw, K, ncols, WT, mode, roff, scr, it, lane);
; }
; __device__ __forceinline__ void conv_w13(const float* w1, const float* w3, const float* g, unsigned char* ws, LAS float* scr, int lane, int gw, int NGW) {
;     bf16* W13 = (bf16*)(ws + WS_W13);
;     conv_mat(w1, g, DFF, DM, DFF, W13, 1, 0, scr, lane, gw, NGW);
;     conv_mat(w3, g, DFF, DM, DFF, W13, 1, 16, scr, lane, (gw + NGW / 2) % NGW, NGW);
; }
; __global__ void __launch_bounds__(NWAVES * 64, 2) mk_fwd(Args args) {
;     ...
;         { const float* win = kin(10); bf16* WIN = (bf16*)(ws + WS_WIN);
;           conv_mat(win, nullptr, NIN, DM, 2560, WIN, 0, 0, SCR_, F.lane, (GW_ + NGW / 2) % NGW, NGW);
;           conv_mat(win + 2560, nullptr, NIN, DM, 512, WIN, 1, 2560, SCR_, F.lane, (GW_ + NGW / 8) % NGW, NGW);
;           conv_mat(win + 3072, nullptr, NIN, DM, 512, WIN, 1, 2560 + 16, SCR_, F.lane, (GW_ + 3 * (NGW / 8)) % NGW, NGW);
;           conv_mat(win + 3584, nullptr, NIN, DM, 2048, WIN, 0, 3584, SCR_, F.lane, (GW_ + 3 * (NGW / 4)) % NGW, NGW); }
.Lcw_p0_loop:
	s_add_u32 s10, s10, s11
	s_cmp_lt_u32 s10, 5632
	s_cbranch_scc0 .Lcw_p0_lastA
	s_cmp_lt_u32 s10, 1408
	s_cbranch_scc1 .Lcw_p0_i1_c0
	s_cmp_lt_u32 s10, 2816
	s_cbranch_scc1 .Lcw_p0_i1_c1
	s_cmp_lt_u32 s10, 4096
	s_cbranch_scc1 .Lcw_p0_i1_c2
	s_cmp_lt_u32 s10, 4352
	s_cbranch_scc1 .Lcw_p0_i1_c3
	s_cmp_lt_u32 s10, 4608
	s_cbranch_scc1 .Lcw_p0_i1_c4
.Lcw_p0_i1_c5:
	s_load_dwordx2 s[8:9], s[0:1], 0x50
	s_sub_u32 s14, s10, 4608
	s_lshr_b32 s15, s14, 6
	s_and_b32 s16, s14, 63
	s_mul_i32 s17, s15, 0x160000
	s_lshl_b32 s19, s16, 7
	s_add_u32 s17, s17, s19
	s_add_u32 s17, s17, 0x3800
	s_mov_b32 s3, 0x5800
	s_mul_i32 s46, s16, 0x10000
	s_lshl_b32 s47, s15, 7
	s_add_u32 s46, s46, s47
	s_add_u32 s46, s46, 0x800000
	s_add_u32 s40, s22, s46
	s_addc_u32 s41, s23, 0
	s_mov_b32 s42, 0x800
	s_mov_b64 s[44:45], 0
	s_branch .Lcw_p0_i1_go
.Lcw_p0_i1_c4:
	s_load_dwordx2 s[8:9], s[0:1], 0x50
	s_sub_u32 s14, s10, 4352
	s_lshr_b32 s15, s14, 4
	s_and_b32 s16, s14, 15
	s_mul_i32 s17, s15, 0x160000
	s_lshl_b32 s19, s16, 7
	s_add_u32 s17, s17, s19
	s_add_u32 s17, s17, 0x3000
	s_mov_b32 s3, 0x5800
	s_mul_i32 s46, s16, 0x20000
	s_lshl_b32 s47, s15, 7
	s_add_u32 s46, s46, s47
	s_add_u32 s46, s46, 0x608000
	s_add_u32 s40, s22, s46
	s_addc_u32 s41, s23, 0
	s_mov_b32 s42, 0x800
	s_mov_b64 s[44:45], -1
	s_branch .Lcw_p0_i1_go
.Lcw_p0_i1_c3:
	s_load_dwordx2 s[8:9], s[0:1], 0x50
	s_sub_u32 s14, s10, 4096
	s_lshr_b32 s15, s14, 4
	s_and_b32 s16, s14, 15
	s_mul_i32 s17, s15, 0x160000
	s_lshl_b32 s19, s16, 7
	s_add_u32 s17, s17, s19
	s_add_u32 s17, s17, 0x2800
	s_mov_b32 s3, 0x5800
	s_mul_i32 s46, s16, 0x20000
	s_lshl_b32 s47, s15, 7
	s_add_u32 s46, s46, s47
	s_add_u32 s46, s46, 0x600000
	s_add_u32 s40, s22, s46
	s_addc_u32 s41, s23, 0
	s_mov_b32 s42, 0x800
	s_mov_b64 s[44:45], -1
	s_branch .Lcw_p0_i1_go
.Lcw_p0_i1_c2:
	s_load_dwordx2 s[8:9], s[0:1], 0x50
	s_sub_u32 s14, s10, 2816
	s_mul_hi_u32 s15, s14, 0x3333334
	s_mul_i32 s16, s15, 80
	s_sub_u32 s16, s14, s16
	s_mul_i32 s17, s15, 0x160000
	s_lshl_b32 s19, s16, 7
	s_add_u32 s17, s17, s19
	s_mov_b32 s3, 0x5800
	s_mul_i32 s46, s16, 0x10000
	s_lshl_b32 s47, s15, 7
	s_add_u32 s46, s46, s47
	s_add_u32 s46, s46, 0x100000
	s_add_u32 s40, s22, s46
	s_addc_u32 s41, s23, 0
	s_mov_b32 s42, 0x800
	s_mov_b64 s[44:45], 0
	s_branch .Lcw_p0_i1_go

; #define GAS __attribute__((address_space(1)))
; #define LAS __attribute__((address_space(3)))
; #define LDS_WAIT() asm volatile("s_waitcnt lgkmcnt(0)" ::: "memory")
; __device__ __forceinline__ unsigned pk2(float lo, float hi) { const f32x2_t_ v = {lo, hi}; return __builtin_bit_cast(unsigned, __builtin_convertvector(v, bf16x2_t_)); }
; __device__ __forceinline__ void transpose_item(const float* W, const float* g, int ldw, int K, int ncols, bf16* WT, int mode, int roff, LAS float* scr, int item, int lane) {
;     const int nblk = ncols / 32, kb = item / nblk, nb = item % nblk, k0 = 64 * kb, n0 = 32 * nb;
;     const float g0 = g ? g[k0 + lane] : 1.0f;
; #pragma unroll 8
;     for (int i = 0; i < 32; ++i) { const int kk = 2 * i + (lane >> 5); scr[kk * 33 + (lane & 31)] = W[(size_t)(k0 + kk) * ldw + n0 + (lane & 31)] * __shfl(g0, kk); }
;     LDS_WAIT(); asm volatile("" ::: "memory");
;     const int c = lane & 7;
; #pragma unroll
;     for (int j = 0; j < 4; ++j) { const int n = (lane >> 3) + 8 * j; const LAS float* s = scr + (8 * c) * 33 + n;
;         v4u o; o.x = pk2(s[0 * 33], s[1 * 33]); o.y = pk2(s[2 * 33], s[3 * 33]); o.z = pk2(s[4 * 33], s[5 * 33]); o.w = pk2(s[6 * 33], s[7 * 33]);
;         const int jc = n0 + n; const int drow = mode ? roff + ((jc >> 4) << 5) + (jc & 15) : roff + jc;
;         *(GAS v4u*)(WT + (size_t)drow * K + k0 + 8 * c) = o; }
;     LDS_WAIT(); asm volatile("" ::: "memory");
; }
.Lcw_p0_pA:
	s_mov_b32 s13, 0
	ds_write_b32 v4, v16
	ds_write_b32 v4, v17 offset:4
	ds_write_b32 v4, v18 offset:8
	ds_write_b32 v4, v19 offset:12
	ds_write_b32 v4, v20 offset:1056
	ds_write_b32 v4, v21 offset:1060
	ds_write_b32 v4, v22 offset:1064
	ds_write_b32 v4, v23 offset:1068
	ds_write_b32 v4, v24 offset:2112
	ds_write_b32 v4, v25 offset:2116
	ds_write_b32 v4, v26 offset:2120
	ds_write_b32 v4, v27 offset:2124
	ds_write_b32 v4, v28 offset:3168
	ds_write_b32 v4, v29 offset:3172
	ds_write_b32 v4, v30 offset:3176
	ds_write_b32 v4, v31 offset:3180
	ds_write_b32 v4, v32 offset:4224
	ds_write_b32 v4, v33 offset:4228
	ds_write_b32 v4, v34 offset:4232
	ds_write_b32 v4, v35 offset:4236
	ds_write_b32 v4, v36 offset:5280
	ds_write_b32 v4, v37 offset:5284
	ds_write_b32 v4, v38 offset:5288
	ds_write_b32 v4, v39 offset:5292
	ds_write_b32 v4, v40 offset:6336
	ds_write_b32 v4, v41 offset:6340
	ds_write_b32 v4, v42 offset:6344
	ds_write_b32 v4, v43 offset:6348
	ds_write_b32 v4, v44 offset:7392
	ds_write_b32 v4, v45 offset:7396
	ds_write_b32 v4, v46 offset:7400
	ds_write_b32 v4, v47 offset:7404
	v_cndmask_b32_e64 v15, v6, v10, s[38:39]
	v_mad_u32_u24 v128, v15, s36, v3
	v_cndmask_b32_e64 v15, v7, v11, s[38:39]
	v_mad_u32_u24 v129, v15, s36, v3
	v_cndmask_b32_e64 v15, v8, v12, s[38:39]
	v_mad_u32_u24 v130, v15, s36, v3
	v_cndmask_b32_e64 v15, v9, v13, s[38:39]
	v_mad_u32_u24 v131, v15, s36, v3
	s_waitcnt lgkmcnt(0)
	ds_read2_b32 v[80:81], v5 offset0:0 offset1:33
	ds_read2_b32 v[82:83], v5 offset0:66 offset1:99
	ds_read2_b32 v[84:85], v5 offset0:132 offset1:165
	ds_read2_b32 v[86:87], v5 offset0:198 offset1:231
	ds_read2_b32 v[88:89], v5 offset0:8 offset1:41
	ds_read2_b32 v[90:91], v5 offset0:74 offset1:107
	ds_read2_b32 v[92:93], v5 offset0:140 offset1:173
	ds_read2_b32 v[94:95], v5 offset0:206 offset1:239
	ds_read2_b32 v[96:97], v5 offset0:16 offset1:49
	ds_read2_b32 v[98:99], v5 offset0:82 offset1:115
	ds_read2_b32 v[100:101], v5 offset0:148 offset1:181
	ds_read2_b32 v[102:103], v5 offset0:214 offset1:247
	ds_read2_b32 v[104:105], v5 offset0:24 offset1:57
	ds_read2_b32 v[106:107], v5 offset0:90 offset1:123
	ds_read2_b32 v[108:109], v5 offset0:156 offset1:189
	ds_read2_b32 v[110:111], v5 offset0:222 offset1:255
	s_waitcnt lgkmcnt(12)
	v_cvt_pk_bf16_f32 v112, v80, v81
	v_cvt_pk_bf16_f32 v113, v82, v83
	v_cvt_pk_bf16_f32 v114, v84, v85
	v_cvt_pk_bf16_f32 v115, v86, v87
	global_store_dwordx4 v128, v[112:115], s[34:35]
	s_waitcnt lgkmcnt(8)
	v_cvt_pk_bf16_f32 v116, v88, v89
	v_cvt_pk_bf16_f32 v117, v90, v91
	v_cvt_pk_bf16_f32 v118, v92, v93
	v_cvt_pk_bf16_f32 v119, v94, v95
	global_store_dwordx4 v129, v[116:119], s[34:35]
	s_waitcnt lgkmcnt(4)
	v_cvt_pk_bf16_f32 v120, v96, v97
	v_cvt_pk_bf16_f32 v121, v98, v99
	v_cvt_pk_bf16_f32 v122, v100, v101
	v_cvt_pk_bf16_f32 v123, v102, v103
	global_store_dwordx4 v130, v[120:123], s[34:35]
	s_waitcnt lgkmcnt(0)
	v_cvt_pk_bf16_f32 v124, v104, v105
	v_cvt_pk_bf16_f32 v125, v106, v107
	v_cvt_pk_bf16_f32 v126, v108, v109
	v_cvt_pk_bf16_f32 v127, v110, v111
	global_store_dwordx4 v131, v[124:127], s[34:35]
	s_add_u32 s10, s10, s11
	s_cmp_lt_u32 s10, 5632
	s_cbranch_scc0 .Lcw_p0_lastB
	s_cmp_lt_u32 s10, 1408
	s_cbranch_scc1 .Lcw_p0_i2_c0
	s_cmp_lt_u32 s10, 2816
	s_cbranch_scc1 .Lcw_p0_i2_c1
	s_cmp_lt_u32 s10, 4096
	s_cbranch_scc1 .Lcw_p0_i2_c2
	s_cmp_lt_u32 s10, 4352
	s_cbranch_scc1 .Lcw_p0_i2_c3
	s_cmp_lt_u32 s10, 4608
	s_cbranch_scc1 .Lcw_p0_i2_c4

; #define LAS __attribute__((address_space(3)))
; __device__ __forceinline__ void conv_mat(const float* W, const float* g, int ldw, int K, int ncols, bf16* WT, int mode, int roff, LAS float* scr, int lane, int gw, int NGW) {
;     const int nitems = (K / 64) * (ncols / 32);
;     for (int it = gw; it < nitems; it += NGW) transpose_item(W, g, ldw, K, ncols, WT, mode, roff, scr, it, lane);
; }
; __device__ __forceinline__ void conv_w13(const float* w1, const float* w3, const float* g, unsigned char* ws, LAS float* scr, int lane, int gw, int NGW) {
;     bf16* W13 = (bf16*)(ws + WS_W13);
;     conv_mat(w1, g, DFF, DM, DFF, W13, 1, 0, scr, lane, gw, NGW);
;     conv_mat(w3, g, DFF, DM, DFF, W13, 1, 16, scr, lane, (gw + NGW / 2) % NGW, NGW);
; }
; __device__ __forceinline__ void conv_w2(const float* w2, unsigned char* ws, LAS float* scr, int lane, int gw, int NGW) {
;     conv_mat(w2, nullptr, DM, DFF, DM, (bf16*)(ws + WS_W2), 0, 0, scr, lane, gw, NGW);
; }
.Lcw_p1t_i0_c0:
	s_load_dwordx2 s[8:9], s[0:1], 0x40
	s_mov_b32 s14, s10
	s_lshr_b32 s15, s14, 5
	s_and_b32 s16, s14, 31
	s_mul_i32 s17, s15, 0x40000
	s_lshl_b32 s19, s16, 7
	s_add_u32 s17, s17, s19
	s_mov_b32 s3, 0x1000
	s_mul_i32 s46, s16, 0x2c000
	s_lshl_b32 s47, s15, 7
	s_add_u32 s46, s46, s47
	s_add_u32 s46, s46, 0x1b00000
	s_add_u32 s34, s22, s46
	s_addc_u32 s35, s23, 0
	s_mov_b32 s36, 0x1600
	s_mov_b64 s[38:39], 0

; #define LAS __attribute__((address_space(3)))
; __device__ __forceinline__ void conv_mat(const float* W, const float* g, int ldw, int K, int ncols, bf16* WT, int mode, int roff, LAS float* scr, int lane, int gw, int NGW) {
;     const int nitems = (K / 64) * (ncols / 32);
;     for (int it = gw; it < nitems; it += NGW) transpose_item(W, g, ldw, K, ncols, WT, mode, roff, scr, it, lane);
; }
; __device__ __forceinline__ void conv_w13(const float* w1, const float* w3, const float* g, unsigned char* ws, LAS float* scr, int lane, int gw, int NGW) {
;     bf16* W13 = (bf16*)(ws + WS_W13);
;     conv_mat(w1, g, DFF, DM, DFF, W13, 1, 0, scr, lane, gw, NGW);
;     conv_mat(w3, g, DFF, DM, DFF, W13, 1, 16, scr, lane, (gw + NGW / 2) % NGW, NGW);
; }
; __device__ __forceinline__ void conv_w2(const float* w2, unsigned char* ws, LAS float* scr, int lane, int gw, int NGW) {
;     conv_mat(w2, nullptr, DM, DFF, DM, (bf16*)(ws + WS_W2), 0, 0, scr, lane, gw, NGW);
; }
.Lcw_p1t_i1_c0:
	s_load_dwordx2 s[8:9], s[0:1], 0x40
	s_mov_b32 s14, s10
	s_lshr_b32 s15, s14, 5
	s_and_b32 s16, s14, 31
	s_mul_i32 s17, s15, 0x40000
	s_lshl_b32 s19, s16, 7
	s_add_u32 s17, s17, s19
	s_mov_b32 s3, 0x1000
	s_mul_i32 s46, s16, 0x2c000
	s_lshl_b32 s47, s15, 7
	s_add_u32 s46, s46, s47
	s_add_u32 s46, s46, 0x1b00000
	s_add_u32 s40, s22, s46
	s_addc_u32 s41, s23, 0
	s_mov_b32 s42, 0x1600
	s_mov_b64 s[44:45], 0

; #define LDSBAR() do { asm volatile("s_waitcnt lgkmcnt(0)" ::: "memory"); __builtin_amdgcn_s_barrier(); asm volatile("" ::: "memory"); } while (0)
; #define HG_STORE(R, s) do { LAS unsigned char* d_ = ring + (s) * HG_SLOT; *(LAS v4u*)(d_ + 16 * tid) = R.q; if (vload) *(LAS v4u*)(d_ + 16384 + 16 * tid) = R.v; *(LAS v4u*)(d_ + 8192 + 16 * tid) = R.l0; \
;         if (tid < 160) *(LAS v4u*)(d_ + 24576 + 16 * tid) = R.l1; } while (0)
; __device__ __forceinline__ void hg_seq(const Frame& F, unsigned char* ws, const float* s0, float* sout, float* Og, int seq, bool sample, int vs_base, int nvs) {
;     ...
;     if (sample && active) {
; #pragma unroll
;         for (int kb = 0; kb < 8; ++kb)
; #pragma unroll
;             for (int i = 0; i < 4; ++i) S[kb][i] = s0[((size_t)seq * 128 + 16 * kb + 4 * q + i) * 128 + 16 * vs + r];
;     } else {
; #pragma unroll
;         for (int kb = 0; kb < 8; ++kb) S[kb] = (f32x4){0.f, 0.f, 0.f, 0.f};
;     }
;     float* Ob = Og + (size_t)t0 * DA + h * 128;
;     ...
;     HgPre R0, R1, R2, R3, R4, R5;
;     R0.l1 = R0.v = (v4u){0u, 0u, 0u, 0u}; R1.l1 = R1.v = (v4u){0u, 0u, 0u, 0u}; R2.l1 = R2.v = (v4u){0u, 0u, 0u, 0u}; R3.l1 = R3.v = (v4u){0u, 0u, 0u, 0u}; R4.l1 = R4.v = (v4u){0u, 0u, 0u, 0u}; R5.l1 = R5.v = (v4u){0u, 0u, 0u, 0u};
;     HG_LOAD(R0, 0); HG_LOAD(R1, 1); HG_LOAD(R2, 2); HG_LOAD(R3, 3); HG_LOAD(R4, 4);
;     HG_STORE(R0, 0); LDSBAR();
.Lsmpb_p4_done:
	s_add_u32 s6, s10, s36
	s_addc_u32 s7, s11, 0
	v_lshl_add_u64 v[140:141], s[6:7], 0, v[2:3]
	s_lshl_b32 s38, s50, 10
	s_add_i32 s39, s38, 0x4000
	s_add_i32 s40, s38, 0x2000
	s_mov_b32 m0, s38
	s_nop 0
	global_load_lds_dwordx4 v[210:211], off
	s_mov_b32 m0, s39
	s_nop 0
	global_load_lds_dwordx4 v[212:213], off
	s_mov_b32 m0, s40
	s_nop 0
	global_load_lds_dwordx4 v[214:215], off
	s_mov_b32 m0, s37
	s_nop 0
	global_load_lds_dwordx4 v[140:141], off
	v_lshl_add_u64 v[210:211], v[210:211], 0, s[34:35]
	v_lshl_add_u64 v[212:213], v[212:213], 0, s[34:35]
	v_lshl_add_u64 v[214:215], v[214:215], 0, s[34:35]
	v_lshl_add_u64 v[140:141], v[140:141], 0, s[34:35]
	s_add_i32 m0, s38, 0x6c00
	s_nop 0
	global_load_lds_dwordx4 v[210:211], off
	s_add_i32 m0, s39, 0x6c00
	s_nop 0
	global_load_lds_dwordx4 v[212:213], off
	s_add_i32 m0, s40, 0x6c00
	s_nop 0
	global_load_lds_dwordx4 v[214:215], off
	s_add_i32 m0, s37, 0x6c00
	s_nop 0
	global_load_lds_dwordx4 v[140:141], off
	v_lshl_add_u64 v[210:211], v[210:211], 0, s[34:35]
	v_lshl_add_u64 v[212:213], v[212:213], 0, s[34:35]
	v_lshl_add_u64 v[214:215], v[214:215], 0, s[34:35]
	v_lshl_add_u64 v[140:141], v[140:141], 0, s[34:35]
	s_add_i32 m0, s38, 0xd800
	s_nop 0
	global_load_lds_dwordx4 v[210:211], off
	s_add_i32 m0, s39, 0xd800
	s_nop 0
	global_load_lds_dwordx4 v[212:213], off
	s_add_i32 m0, s40, 0xd800
	s_nop 0
	global_load_lds_dwordx4 v[214:215], off
	s_add_i32 m0, s37, 0xd800
	s_nop 0
	global_load_lds_dwordx4 v[140:141], off
	global_load_dwordx4 v[4:7], v200, s[8:9]
	global_load_dwordx4 v[8:11], v201, s[8:9]
	global_load_dwordx4 v[12:15], v202, s[8:9]
	global_load_dwordx4 v[16:19], v203, s[8:9]
	global_load_dwordx4 v[20:23], v204, s[8:9]
	global_load_dwordx4 v[24:27], v205, s[8:9]
	global_load_dwordx4 v[28:31], v206, s[8:9]
	global_load_dwordx4 v[32:35], v207, s[8:9]
	s_add_u32 s8, s8, s34
	s_addc_u32 s9, s9, 0
	global_load_dwordx4 v[36:39], v200, s[8:9]
	global_load_dwordx4 v[40:43], v201, s[8:9]
	global_load_dwordx4 v[44:47], v202, s[8:9]
	global_load_dwordx4 v[48:51], v203, s[8:9]
	global_load_dwordx4 v[52:55], v204, s[8:9]
	global_load_dwordx4 v[56:59], v205, s[8:9]
	global_load_dwordx4 v[60:63], v206, s[8:9]
	global_load_dwordx4 v[64:67], v207, s[8:9]
	s_add_u32 s8, s8, s34
	s_addc_u32 s9, s9, 0
	s_waitcnt vmcnt(8)
	s_barrier
	v_cndmask_b32_e64 v145, v4, v5, s[42:43]
	v_cndmask_b32_e64 v147, v6, v7, s[42:43]
	s_nop 1
	v_mov_b32_dpp v146, v145 quad_perm:[1,0,3,2] row_mask:0xf bank_mask:0xf
	v_mov_b32_dpp v156, v147 quad_perm:[1,0,3,2] row_mask:0xf bank_mask:0xf
	v_cndmask_b32_e64 v5, v5, v146, s[42:43]
	v_cndmask_b32_e64 v4, v146, v4, s[42:43]
	v_cndmask_b32_e64 v7, v7, v156, s[42:43]
	v_cndmask_b32_e64 v6, v156, v6, s[42:43]
	v_cndmask_b32_e64 v145, v4, v6, s[44:45]
	v_cndmask_b32_e64 v147, v5, v7, s[44:45]
	s_nop 1
	v_mov_b32_dpp v146, v145 quad_perm:[2,3,0,1] row_mask:0xf bank_mask:0xf
	v_mov_b32_dpp v156, v147 quad_perm:[2,3,0,1] row_mask:0xf bank_mask:0xf
	v_cndmask_b32_e64 v6, v6, v146, s[44:45]
	v_cndmask_b32_e64 v4, v146, v4, s[44:45]
	v_cndmask_b32_e64 v7, v7, v156, s[44:45]
	v_cndmask_b32_e64 v5, v156, v5, s[44:45]
	v_cndmask_b32_e64 v145, v8, v9, s[42:43]
	v_cndmask_b32_e64 v147, v10, v11, s[42:43]
	s_nop 1
	v_mov_b32_dpp v146, v145 quad_perm:[1,0,3,2] row_mask:0xf bank_mask:0xf
	v_mov_b32_dpp v156, v147 quad_perm:[1,0,3,2] row_mask:0xf bank_mask:0xf
	v_cndmask_b32_e64 v9, v9, v146, s[42:43]
	v_cndmask_b32_e64 v8, v146, v8, s[42:43]
	v_cndmask_b32_e64 v11, v11, v156, s[42:43]
	v_cndmask_b32_e64 v10, v156, v10, s[42:43]
	v_cndmask_b32_e64 v145, v8, v10, s[44:45]
	v_cndmask_b32_e64 v147, v9, v11, s[44:45]
	s_nop 1
	v_mov_b32_dpp v146, v145 quad_perm:[2,3,0,1] row_mask:0xf bank_mask:0xf
	v_mov_b32_dpp v156, v147 quad_perm:[2,3,0,1] row_mask:0xf bank_mask:0xf
	v_cndmask_b32_e64 v10, v10, v146, s[44:45]
	v_cndmask_b32_e64 v8, v146, v8, s[44:45]
	v_cndmask_b32_e64 v11, v11, v156, s[44:45]
	v_cndmask_b32_e64 v9, v156, v9, s[44:45]
	v_cndmask_b32_e64 v145, v12, v13, s[42:43]
	v_cndmask_b32_e64 v147, v14, v15, s[42:43]
	s_nop 1
	v_mov_b32_dpp v146, v145 quad_perm:[1,0,3,2] row_mask:0xf bank_mask:0xf
	v_mov_b32_dpp v156, v147 quad_perm:[1,0,3,2] row_mask:0xf bank_mask:0xf
	v_cndmask_b32_e64 v13, v13, v146, s[42:43]
	v_cndmask_b32_e64 v12, v146, v12, s[42:43]
	v_cndmask_b32_e64 v15, v15, v156, s[42:43]
	v_cndmask_b32_e64 v14, v156, v14, s[42:43]
	v_cndmask_b32_e64 v145, v12, v14, s[44:45]
	v_cndmask_b32_e64 v147, v13, v15, s[44:45]
	s_nop 1
	v_mov_b32_dpp v146, v145 quad_perm:[2,3,0,1] row_mask:0xf bank_mask:0xf
	v_mov_b32_dpp v156, v147 quad_perm:[2,3,0,1] row_mask:0xf bank_mask:0xf
	v_cndmask_b32_e64 v14, v14, v146, s[44:45]
	v_cndmask_b32_e64 v12, v146, v12, s[44:45]
	v_cndmask_b32_e64 v15, v15, v156, s[44:45]
	v_cndmask_b32_e64 v13, v156, v13, s[44:45]
	v_cndmask_b32_e64 v145, v16, v17, s[42:43]
	v_cndmask_b32_e64 v147, v18, v19, s[42:43]
	s_nop 1
	v_mov_b32_dpp v146, v145 quad_perm:[1,0,3,2] row_mask:0xf bank_mask:0xf
	v_mov_b32_dpp v156, v147 quad_perm:[1,0,3,2] row_mask:0xf bank_mask:0xf
	v_cndmask_b32_e64 v17, v17, v146, s[42:43]
	v_cndmask_b32_e64 v16, v146, v16, s[42:43]
	v_cndmask_b32_e64 v19, v19, v156, s[42:43]
	v_cndmask_b32_e64 v18, v156, v18, s[42:43]
	v_cndmask_b32_e64 v145, v16, v18, s[44:45]
	v_cndmask_b32_e64 v147, v17, v19, s[44:45]
	s_nop 1
	v_mov_b32_dpp v146, v145 quad_perm:[2,3,0,1] row_mask:0xf bank_mask:0xf
	v_mov_b32_dpp v156, v147 quad_perm:[2,3,0,1] row_mask:0xf bank_mask:0xf
	v_cndmask_b32_e64 v18, v18, v146, s[44:45]
	v_cndmask_b32_e64 v16, v146, v16, s[44:45]
	v_cndmask_b32_e64 v19, v19, v156, s[44:45]
	v_cndmask_b32_e64 v17, v156, v17, s[44:45]
; #define LAS __attribute__((address_space(3)))
; __device__ __forceinline__ unsigned pk2(float lo, float hi) { const f32x2_t_ v = {lo, hi}; return __builtin_bit_cast(unsigned, __builtin_convertvector(v, bf16x2_t_)); }
; __device__ __forceinline__ void hg_chunk(const LAS unsigned char* sl, f32x4 (&S)[8], float* Orow, int nvalid, int vs, int lane) {
;     const int r = lane & 15, q = lane >> 4;
;     const bf16x8 vfr = *(const LAS bf16x8*)(sl + 16384 + ((vs * 64 + lane) << 4));
;     f32x4 o0 = {0.f, 0.f, 0.f, 0.f}, o1 = {0.f, 0.f, 0.f, 0.f};
;     { const bf16x8 s0 = *(const LAS bf16x8*)(sl + 24576 + (lane << 4)), s1 = *(const LAS bf16x8*)(sl + 24576 + ((64 + lane) << 4));
;       o0 = __builtin_amdgcn_mfma_f32_16x16x32_bf16(s0, vfr, o0, 0, 0, 0); o1 = __builtin_amdgcn_mfma_f32_16x16x32_bf16(s1, vfr, o1, 0, 0, 0); }
; #pragma unroll
;     for (int m = 0; m < 4; ++m) {
;         v4u sw; sw.x = pk2(S[2 * m][0], S[2 * m][1]); sw.y = pk2(S[2 * m][2], S[2 * m][3]); sw.z = pk2(S[2 * m + 1][0], S[2 * m + 1][1]); sw.w = pk2(S[2 * m + 1][2], S[2 * m + 1][3]);
;         const bf16x8 sb = __builtin_bit_cast(bf16x8, sw);
;         const bf16x8 a0 = *(const LAS bf16x8*)(sl + ((m * 64 + lane) << 4)), a1 = *(const LAS bf16x8*)(sl + (((4 + m) * 64 + lane) << 4));
;         o0 = __builtin_amdgcn_mfma_f32_16x16x32_bf16(a0, sb, o0, 0, 0, 0); o1 = __builtin_amdgcn_mfma_f32_16x16x32_bf16(a1, sb, o1, 0, 0, 0);
;     }
; #pragma unroll
;     for (int i = 0; i < 4; ++i) { const int c0 = 4 * q + i;
;         if (c0 < nvalid) Orow[(size_t)c0 * DA + 16 * vs + r] = o0[i];
;         if (c0 + 16 < nvalid) Orow[(size_t)(c0 + 16) * DA + 16 * vs + r] = o1[i]; }
; #pragma unroll
;     for (int kb = 0; kb < 8; ++kb) { const f32x4 d = *(const LAS f32x4*)(sl + 26624 + ((16 * kb + 4 * q) << 2));
;         const bf16x8 ke = *(const LAS bf16x8*)(sl + 8192 + ((kb * 64 + lane) << 4));
;         S[kb] = __builtin_amdgcn_mfma_f32_16x16x32_bf16(ke, vfr, S[kb] * d, 0, 0, 0); }
	v_cndmask_b32_e64 v145, v20, v21, s[42:43]
	v_cndmask_b32_e64 v147, v22, v23, s[42:43]
	s_nop 1
	v_mov_b32_dpp v146, v145 quad_perm:[1,0,3,2] row_mask:0xf bank_mask:0xf
	v_mov_b32_dpp v156, v147 quad_perm:[1,0,3,2] row_mask:0xf bank_mask:0xf
	v_cndmask_b32_e64 v21, v21, v146, s[42:43]
	v_cndmask_b32_e64 v20, v146, v20, s[42:43]
	v_cndmask_b32_e64 v23, v23, v156, s[42:43]
	v_cndmask_b32_e64 v22, v156, v22, s[42:43]
	v_cndmask_b32_e64 v145, v20, v22, s[44:45]
	v_cndmask_b32_e64 v147, v21, v23, s[44:45]
	s_nop 1
	v_mov_b32_dpp v146, v145 quad_perm:[2,3,0,1] row_mask:0xf bank_mask:0xf
	v_mov_b32_dpp v156, v147 quad_perm:[2,3,0,1] row_mask:0xf bank_mask:0xf
	v_cndmask_b32_e64 v22, v22, v146, s[44:45]
	v_cndmask_b32_e64 v20, v146, v20, s[44:45]
	v_cndmask_b32_e64 v23, v23, v156, s[44:45]
	v_cndmask_b32_e64 v21, v156, v21, s[44:45]
	v_cndmask_b32_e64 v145, v24, v25, s[42:43]
	v_cndmask_b32_e64 v147, v26, v27, s[42:43]
	s_nop 1
	v_mov_b32_dpp v146, v145 quad_perm:[1,0,3,2] row_mask:0xf bank_mask:0xf
	v_mov_b32_dpp v156, v147 quad_perm:[1,0,3,2] row_mask:0xf bank_mask:0xf
	v_cndmask_b32_e64 v25, v25, v146, s[42:43]
	v_cndmask_b32_e64 v24, v146, v24, s[42:43]
	v_cndmask_b32_e64 v27, v27, v156, s[42:43]
	v_cndmask_b32_e64 v26, v156, v26, s[42:43]
	v_cndmask_b32_e64 v145, v24, v26, s[44:45]
	v_cndmask_b32_e64 v147, v25, v27, s[44:45]
	s_nop 1
	v_mov_b32_dpp v146, v145 quad_perm:[2,3,0,1] row_mask:0xf bank_mask:0xf
	v_mov_b32_dpp v156, v147 quad_perm:[2,3,0,1] row_mask:0xf bank_mask:0xf
	v_cndmask_b32_e64 v26, v26, v146, s[44:45]
	v_cndmask_b32_e64 v24, v146, v24, s[44:45]
	v_cndmask_b32_e64 v27, v27, v156, s[44:45]
	v_cndmask_b32_e64 v25, v156, v25, s[44:45]
	v_cndmask_b32_e64 v145, v28, v29, s[42:43]
	v_cndmask_b32_e64 v147, v30, v31, s[42:43]
	s_nop 1
	v_mov_b32_dpp v146, v145 quad_perm:[1,0,3,2] row_mask:0xf bank_mask:0xf
	v_mov_b32_dpp v156, v147 quad_perm:[1,0,3,2] row_mask:0xf bank_mask:0xf
	v_cndmask_b32_e64 v29, v29, v146, s[42:43]
	v_cndmask_b32_e64 v28, v146, v28, s[42:43]
	v_cndmask_b32_e64 v31, v31, v156, s[42:43]
	v_cndmask_b32_e64 v30, v156, v30, s[42:43]
	v_cndmask_b32_e64 v145, v28, v30, s[44:45]
	v_cndmask_b32_e64 v147, v29, v31, s[44:45]
	s_nop 1
	v_mov_b32_dpp v146, v145 quad_perm:[2,3,0,1] row_mask:0xf bank_mask:0xf
	v_mov_b32_dpp v156, v147 quad_perm:[2,3,0,1] row_mask:0xf bank_mask:0xf
	v_cndmask_b32_e64 v30, v30, v146, s[44:45]
	v_cndmask_b32_e64 v28, v146, v28, s[44:45]
	v_cndmask_b32_e64 v31, v31, v156, s[44:45]
	v_cndmask_b32_e64 v29, v156, v29, s[44:45]
	v_cndmask_b32_e64 v145, v32, v33, s[42:43]
	v_cndmask_b32_e64 v147, v34, v35, s[42:43]
	s_nop 1
	v_mov_b32_dpp v146, v145 quad_perm:[1,0,3,2] row_mask:0xf bank_mask:0xf
	v_mov_b32_dpp v156, v147 quad_perm:[1,0,3,2] row_mask:0xf bank_mask:0xf
	v_cndmask_b32_e64 v33, v33, v146, s[42:43]
	v_cndmask_b32_e64 v32, v146, v32, s[42:43]
	v_cndmask_b32_e64 v35, v35, v156, s[42:43]
	v_cndmask_b32_e64 v34, v156, v34, s[42:43]
	v_cndmask_b32_e64 v145, v32, v34, s[44:45]
	v_cndmask_b32_e64 v147, v33, v35, s[44:45]
	s_nop 1
	v_mov_b32_dpp v146, v145 quad_perm:[2,3,0,1] row_mask:0xf bank_mask:0xf
	v_mov_b32_dpp v156, v147 quad_perm:[2,3,0,1] row_mask:0xf bank_mask:0xf
	v_cndmask_b32_e64 v34, v34, v146, s[44:45]
	v_cndmask_b32_e64 v32, v146, v32, s[44:45]
	v_cndmask_b32_e64 v35, v35, v156, s[44:45]
	v_cndmask_b32_e64 v33, v156, v33, s[44:45]
	v_mov_b32_e32 v1, v142
	v_mov_b32_e32 v2, v143
	v_mov_b32_e32 v3, v144
	ds_read_b128 v[164:167], v3 offset:26624
	ds_read_b128 v[168:171], v3 offset:26688
	ds_read_b128 v[172:175], v3 offset:26752
	ds_read_b128 v[176:179], v3 offset:26816
	ds_read_b128 v[180:183], v3 offset:26880
	ds_read_b128 v[184:187], v3 offset:26944
	ds_read_b128 v[148:151], v3 offset:27008
	ds_read_b128 v[152:155], v3 offset:27072
	ds_read_b128 v[84:87], v2 offset:16384
	ds_read_b128 v[88:91], v1 offset:24576
	ds_read_b128 v[92:95], v1 offset:0
	ds_read_b128 v[96:99], v1 offset:1024
	ds_read_b128 v[100:103], v1 offset:2048
	ds_read_b128 v[104:107], v1 offset:3072
	v_cvt_pk_bf16_f32 v68, v4, v5
	v_cvt_pk_bf16_f32 v69, v6, v7
	v_cvt_pk_bf16_f32 v70, v8, v9
	v_cvt_pk_bf16_f32 v71, v10, v11
	v_cvt_pk_bf16_f32 v72, v12, v13
	v_cvt_pk_bf16_f32 v73, v14, v15
	v_cvt_pk_bf16_f32 v74, v16, v17
	v_cvt_pk_bf16_f32 v75, v18, v19
	v_cvt_pk_bf16_f32 v76, v20, v21
	v_cvt_pk_bf16_f32 v77, v22, v23
	v_cvt_pk_bf16_f32 v78, v24, v25
	v_cvt_pk_bf16_f32 v79, v26, v27
	v_cvt_pk_bf16_f32 v80, v28, v29
	v_cvt_pk_bf16_f32 v81, v30, v31
	v_cvt_pk_bf16_f32 v82, v32, v33
	v_cvt_pk_bf16_f32 v83, v34, v35
	s_waitcnt lgkmcnt(6)
	v_pk_mul_f32 v[4:5], v[4:5], v[164:165]
	v_pk_mul_f32 v[6:7], v[6:7], v[166:167]
	v_pk_mul_f32 v[8:9], v[8:9], v[168:169]
	v_pk_mul_f32 v[10:11], v[10:11], v[170:171]
	v_pk_mul_f32 v[12:13], v[12:13], v[172:173]
	v_pk_mul_f32 v[14:15], v[14:15], v[174:175]
	v_pk_mul_f32 v[16:17], v[16:17], v[176:177]
	v_pk_mul_f32 v[18:19], v[18:19], v[178:179]
	v_pk_mul_f32 v[20:21], v[20:21], v[180:181]
	v_pk_mul_f32 v[22:23], v[22:23], v[182:183]
	v_pk_mul_f32 v[24:25], v[24:25], v[184:185]
	v_pk_mul_f32 v[26:27], v[26:27], v[186:187]
	v_pk_mul_f32 v[28:29], v[28:29], v[148:149]
	v_pk_mul_f32 v[30:31], v[30:31], v[150:151]
	v_pk_mul_f32 v[32:33], v[32:33], v[152:153]
	v_pk_mul_f32 v[34:35], v[34:35], v[154:155]
	ds_read_b128 v[108:111], v1 offset:8192
	ds_read_b128 v[112:115], v1 offset:9216
	ds_read_b128 v[116:119], v1 offset:10240
	ds_read_b128 v[120:123], v1 offset:11264
	ds_read_b128 v[124:127], v1 offset:12288
	ds_read_b128 v[128:131], v1 offset:13312
	ds_read_b128 v[132:135], v1 offset:14336
	ds_read_b128 v[136:139], v1 offset:15360
	s_waitcnt lgkmcnt(12)
; #define LAS __attribute__((address_space(3)))
; __device__ __forceinline__ unsigned pk2(float lo, float hi) { const f32x2_t_ v = {lo, hi}; return __builtin_bit_cast(unsigned, __builtin_convertvector(v, bf16x2_t_)); }
; __device__ __forceinline__ void hg_chunk(const LAS unsigned char* sl, f32x4 (&S)[8], float* Orow, int nvalid, int vs, int lane) {
;     const int r = lane & 15, q = lane >> 4;
;     const bf16x8 vfr = *(const LAS bf16x8*)(sl + 16384 + ((vs * 64 + lane) << 4));
;     f32x4 o0 = {0.f, 0.f, 0.f, 0.f}, o1 = {0.f, 0.f, 0.f, 0.f};
;     { const bf16x8 s0 = *(const LAS bf16x8*)(sl + 24576 + (lane << 4)), s1 = *(const LAS bf16x8*)(sl + 24576 + ((64 + lane) << 4));
;       o0 = __builtin_amdgcn_mfma_f32_16x16x32_bf16(s0, vfr, o0, 0, 0, 0); o1 = __builtin_amdgcn_mfma_f32_16x16x32_bf16(s1, vfr, o1, 0, 0, 0); }
; #pragma unroll
;     for (int m = 0; m < 4; ++m) {
;         v4u sw; sw.x = pk2(S[2 * m][0], S[2 * m][1]); sw.y = pk2(S[2 * m][2], S[2 * m][3]); sw.z = pk2(S[2 * m + 1][0], S[2 * m + 1][1]); sw.w = pk2(S[2 * m + 1][2], S[2 * m + 1][3]);
;         const bf16x8 sb = __builtin_bit_cast(bf16x8, sw);
;         const bf16x8 a0 = *(const LAS bf16x8*)(sl + ((m * 64 + lane) << 4)), a1 = *(const LAS bf16x8*)(sl + (((4 + m) * 64 + lane) << 4));
;         o0 = __builtin_amdgcn_mfma_f32_16x16x32_bf16(a0, sb, o0, 0, 0, 0); o1 = __builtin_amdgcn_mfma_f32_16x16x32_bf16(a1, sb, o1, 0, 0, 0);
;     }
; #pragma unroll
;     for (int i = 0; i < 4; ++i) { const int c0 = 4 * q + i;
;         if (c0 < nvalid) Orow[(size_t)c0 * DA + 16 * vs + r] = o0[i];
;         if (c0 + 16 < nvalid) Orow[(size_t)(c0 + 16) * DA + 16 * vs + r] = o1[i]; }
; #pragma unroll
;     for (int kb = 0; kb < 8; ++kb) { const f32x4 d = *(const LAS f32x4*)(sl + 26624 + ((16 * kb + 4 * q) << 2));
;         const bf16x8 ke = *(const LAS bf16x8*)(sl + 8192 + ((kb * 64 + lane) << 4));
;         S[kb] = __builtin_amdgcn_mfma_f32_16x16x32_bf16(ke, vfr, S[kb] * d, 0, 0, 0); }
; __device__ __forceinline__ void hg_seq(const Frame& F, unsigned char* ws, const float* s0, float* sout, float* Og, int seq, bool sample, int vs_base, int nvs) {
;     ...
;     if (active) {
; #pragma unroll
;     for (int kb = 0; kb < 8; ++kb)
; #pragma unroll
;         for (int i = 0; i < 4; ++i) sout[((size_t)seq * 128 + 16 * kb + 4 * q + i) * 128 + 16 * vs + r] = S[kb][i];
	v_mfma_f32_16x16x32_bf16 v[196:199], v[88:91], v[84:87], 0
	s_waitcnt lgkmcnt(11)
	v_mfma_f32_16x16x32_bf16 v[196:199], v[92:95], v[68:71], v[196:199]
	s_waitcnt lgkmcnt(10)
	v_mfma_f32_16x16x32_bf16 v[196:199], v[96:99], v[72:75], v[196:199]
	s_waitcnt lgkmcnt(9)
	v_mfma_f32_16x16x32_bf16 v[196:199], v[100:103], v[76:79], v[196:199]
	s_waitcnt lgkmcnt(8)
	v_mfma_f32_16x16x32_bf16 v[196:199], v[104:107], v[80:83], v[196:199]
	s_waitcnt lgkmcnt(7)
	v_mfma_f32_16x16x32_bf16 v[4:7], v[108:111], v[84:87], v[4:7]
	s_waitcnt lgkmcnt(6)
	v_mfma_f32_16x16x32_bf16 v[8:11], v[112:115], v[84:87], v[8:11]
	s_waitcnt lgkmcnt(5)
	v_mfma_f32_16x16x32_bf16 v[12:15], v[116:119], v[84:87], v[12:15]
	s_waitcnt lgkmcnt(4)
	v_mfma_f32_16x16x32_bf16 v[16:19], v[120:123], v[84:87], v[16:19]
	s_waitcnt lgkmcnt(3)
	v_mfma_f32_16x16x32_bf16 v[20:23], v[124:127], v[84:87], v[20:23]
	s_waitcnt lgkmcnt(2)
	v_mfma_f32_16x16x32_bf16 v[24:27], v[128:131], v[84:87], v[24:27]
	s_waitcnt lgkmcnt(1)
	v_mfma_f32_16x16x32_bf16 v[28:31], v[132:135], v[84:87], v[28:31]
	s_waitcnt lgkmcnt(0)
	v_mfma_f32_16x16x32_bf16 v[32:35], v[136:139], v[84:87], v[32:35]
	s_mov_b32 exec_hi, 0
	global_store_dword v208, v196, s[12:13]
	global_store_dword v208, v197, s[12:13] offset:2048
	global_store_dword v209, v198, s[12:13]
	global_store_dword v209, v199, s[12:13] offset:2048
	s_mov_b64 exec, -1
	s_add_u32 s12, s12, 0x80000
	s_addc_u32 s13, s13, 0
	s_nop 7
	v_cndmask_b32_e64 v145, v4, v5, s[42:43]
	v_cndmask_b32_e64 v147, v6, v7, s[42:43]
	s_nop 1
	v_mov_b32_dpp v146, v145 quad_perm:[1,0,3,2] row_mask:0xf bank_mask:0xf
	v_mov_b32_dpp v156, v147 quad_perm:[1,0,3,2] row_mask:0xf bank_mask:0xf
	v_cndmask_b32_e64 v5, v5, v146, s[42:43]
	v_cndmask_b32_e64 v4, v146, v4, s[42:43]
	v_cndmask_b32_e64 v7, v7, v156, s[42:43]
	v_cndmask_b32_e64 v6, v156, v6, s[42:43]
	v_cndmask_b32_e64 v145, v4, v6, s[44:45]
	v_cndmask_b32_e64 v147, v5, v7, s[44:45]
	s_nop 1
	v_mov_b32_dpp v146, v145 quad_perm:[2,3,0,1] row_mask:0xf bank_mask:0xf
	v_mov_b32_dpp v156, v147 quad_perm:[2,3,0,1] row_mask:0xf bank_mask:0xf
	v_cndmask_b32_e64 v6, v6, v146, s[44:45]
	v_cndmask_b32_e64 v4, v146, v4, s[44:45]
	v_cndmask_b32_e64 v7, v7, v156, s[44:45]
	v_cndmask_b32_e64 v5, v156, v5, s[44:45]
	v_cndmask_b32_e64 v145, v8, v9, s[42:43]
	v_cndmask_b32_e64 v147, v10, v11, s[42:43]
	s_nop 1
	v_mov_b32_dpp v146, v145 quad_perm:[1,0,3,2] row_mask:0xf bank_mask:0xf
	v_mov_b32_dpp v156, v147 quad_perm:[1,0,3,2] row_mask:0xf bank_mask:0xf
	v_cndmask_b32_e64 v9, v9, v146, s[42:43]
	v_cndmask_b32_e64 v8, v146, v8, s[42:43]
	v_cndmask_b32_e64 v11, v11, v156, s[42:43]
	v_cndmask_b32_e64 v10, v156, v10, s[42:43]
	v_cndmask_b32_e64 v145, v8, v10, s[44:45]
	v_cndmask_b32_e64 v147, v9, v11, s[44:45]
	s_nop 1
	v_mov_b32_dpp v146, v145 quad_perm:[2,3,0,1] row_mask:0xf bank_mask:0xf
	v_mov_b32_dpp v156, v147 quad_perm:[2,3,0,1] row_mask:0xf bank_mask:0xf
	v_cndmask_b32_e64 v10, v10, v146, s[44:45]
	v_cndmask_b32_e64 v8, v146, v8, s[44:45]
	v_cndmask_b32_e64 v11, v11, v156, s[44:45]
	v_cndmask_b32_e64 v9, v156, v9, s[44:45]
	v_cndmask_b32_e64 v145, v12, v13, s[42:43]
	v_cndmask_b32_e64 v147, v14, v15, s[42:43]
	s_nop 1
	v_mov_b32_dpp v146, v145 quad_perm:[1,0,3,2] row_mask:0xf bank_mask:0xf
	v_mov_b32_dpp v156, v147 quad_perm:[1,0,3,2] row_mask:0xf bank_mask:0xf
	v_cndmask_b32_e64 v13, v13, v146, s[42:43]
	v_cndmask_b32_e64 v12, v146, v12, s[42:43]
	v_cndmask_b32_e64 v15, v15, v156, s[42:43]
	v_cndmask_b32_e64 v14, v156, v14, s[42:43]
	v_cndmask_b32_e64 v145, v12, v14, s[44:45]
	v_cndmask_b32_e64 v147, v13, v15, s[44:45]
	s_nop 1
	v_mov_b32_dpp v146, v145 quad_perm:[2,3,0,1] row_mask:0xf bank_mask:0xf
	v_mov_b32_dpp v156, v147 quad_perm:[2,3,0,1] row_mask:0xf bank_mask:0xf
	v_cndmask_b32_e64 v14, v14, v146, s[44:45]
	v_cndmask_b32_e64 v12, v146, v12, s[44:45]
	v_cndmask_b32_e64 v15, v15, v156, s[44:45]
	v_cndmask_b32_e64 v13, v156, v13, s[44:45]
	v_cndmask_b32_e64 v145, v16, v17, s[42:43]
	v_cndmask_b32_e64 v147, v18, v19, s[42:43]
	s_nop 1
	v_mov_b32_dpp v146, v145 quad_perm:[1,0,3,2] row_mask:0xf bank_mask:0xf
	v_mov_b32_dpp v156, v147 quad_perm:[1,0,3,2] row_mask:0xf bank_mask:0xf
	v_cndmask_b32_e64 v17, v17, v146, s[42:43]
	v_cndmask_b32_e64 v16, v146, v16, s[42:43]
	v_cndmask_b32_e64 v19, v19, v156, s[42:43]
	v_cndmask_b32_e64 v18, v156, v18, s[42:43]
	v_cndmask_b32_e64 v145, v16, v18, s[44:45]
	v_cndmask_b32_e64 v147, v17, v19, s[44:45]
	s_nop 1
	v_mov_b32_dpp v146, v145 quad_perm:[2,3,0,1] row_mask:0xf bank_mask:0xf
	v_mov_b32_dpp v156, v147 quad_perm:[2,3,0,1] row_mask:0xf bank_mask:0xf
	v_cndmask_b32_e64 v18, v18, v146, s[44:45]
	v_cndmask_b32_e64 v16, v146, v16, s[44:45]
	v_cndmask_b32_e64 v19, v19, v156, s[44:45]
	v_cndmask_b32_e64 v17, v156, v17, s[44:45]
	v_cndmask_b32_e64 v145, v20, v21, s[42:43]
	v_cndmask_b32_e64 v147, v22, v23, s[42:43]
	s_nop 1
	v_mov_b32_dpp v146, v145 quad_perm:[1,0,3,2] row_mask:0xf bank_mask:0xf
	v_mov_b32_dpp v156, v147 quad_perm:[1,0,3,2] row_mask:0xf bank_mask:0xf
	v_cndmask_b32_e64 v21, v21, v146, s[42:43]
	v_cndmask_b32_e64 v20, v146, v20, s[42:43]
	v_cndmask_b32_e64 v23, v23, v156, s[42:43]
	v_cndmask_b32_e64 v22, v156, v22, s[42:43]
	v_cndmask_b32_e64 v145, v20, v22, s[44:45]
	v_cndmask_b32_e64 v147, v21, v23, s[44:45]
	s_nop 1
	v_mov_b32_dpp v146, v145 quad_perm:[2,3,0,1] row_mask:0xf bank_mask:0xf
	v_mov_b32_dpp v156, v147 quad_perm:[2,3,0,1] row_mask:0xf bank_mask:0xf
	v_cndmask_b32_e64 v22, v22, v146, s[44:45]
	v_cndmask_b32_e64 v20, v146, v20, s[44:45]
	v_cndmask_b32_e64 v23, v23, v156, s[44:45]
	v_cndmask_b32_e64 v21, v156, v21, s[44:45]
	v_cndmask_b32_e64 v145, v24, v25, s[42:43]
; __device__ __forceinline__ void hg_seq(const Frame& F, unsigned char* ws, const float* s0, float* sout, float* Og, int seq, bool sample, int vs_base, int nvs) {
;     ...
;     if (sample && active) {
; #pragma unroll
;         for (int kb = 0; kb < 8; ++kb)
; #pragma unroll
;             for (int i = 0; i < 4; ++i) S[kb][i] = s0[((size_t)seq * 128 + 16 * kb + 4 * q + i) * 128 + 16 * vs + r];
;     ...
;     if (active) {
; #pragma unroll
;     for (int kb = 0; kb < 8; ++kb)
; #pragma unroll
;         for (int i = 0; i < 4; ++i) sout[((size_t)seq * 128 + 16 * kb + 4 * q + i) * 128 + 16 * vs + r] = S[kb][i];
	v_cndmask_b32_e64 v147, v26, v27, s[42:43]
	s_nop 1
	v_mov_b32_dpp v146, v145 quad_perm:[1,0,3,2] row_mask:0xf bank_mask:0xf
	v_mov_b32_dpp v156, v147 quad_perm:[1,0,3,2] row_mask:0xf bank_mask:0xf
	v_cndmask_b32_e64 v25, v25, v146, s[42:43]
	v_cndmask_b32_e64 v24, v146, v24, s[42:43]
	v_cndmask_b32_e64 v27, v27, v156, s[42:43]
	v_cndmask_b32_e64 v26, v156, v26, s[42:43]
	v_cndmask_b32_e64 v145, v24, v26, s[44:45]
	v_cndmask_b32_e64 v147, v25, v27, s[44:45]
	s_nop 1
	v_mov_b32_dpp v146, v145 quad_perm:[2,3,0,1] row_mask:0xf bank_mask:0xf
	v_mov_b32_dpp v156, v147 quad_perm:[2,3,0,1] row_mask:0xf bank_mask:0xf
	v_cndmask_b32_e64 v26, v26, v146, s[44:45]
	v_cndmask_b32_e64 v24, v146, v24, s[44:45]
	v_cndmask_b32_e64 v27, v27, v156, s[44:45]
	v_cndmask_b32_e64 v25, v156, v25, s[44:45]
	v_cndmask_b32_e64 v145, v28, v29, s[42:43]
	v_cndmask_b32_e64 v147, v30, v31, s[42:43]
	s_nop 1
	v_mov_b32_dpp v146, v145 quad_perm:[1,0,3,2] row_mask:0xf bank_mask:0xf
	v_mov_b32_dpp v156, v147 quad_perm:[1,0,3,2] row_mask:0xf bank_mask:0xf
	v_cndmask_b32_e64 v29, v29, v146, s[42:43]
	v_cndmask_b32_e64 v28, v146, v28, s[42:43]
	v_cndmask_b32_e64 v31, v31, v156, s[42:43]
	v_cndmask_b32_e64 v30, v156, v30, s[42:43]
	v_cndmask_b32_e64 v145, v28, v30, s[44:45]
	v_cndmask_b32_e64 v147, v29, v31, s[44:45]
	s_nop 1
	v_mov_b32_dpp v146, v145 quad_perm:[2,3,0,1] row_mask:0xf bank_mask:0xf
	v_mov_b32_dpp v156, v147 quad_perm:[2,3,0,1] row_mask:0xf bank_mask:0xf
	v_cndmask_b32_e64 v30, v30, v146, s[44:45]
	v_cndmask_b32_e64 v28, v146, v28, s[44:45]
	v_cndmask_b32_e64 v31, v31, v156, s[44:45]
	v_cndmask_b32_e64 v29, v156, v29, s[44:45]
	v_cndmask_b32_e64 v145, v32, v33, s[42:43]
	v_cndmask_b32_e64 v147, v34, v35, s[42:43]
	s_nop 1
	v_mov_b32_dpp v146, v145 quad_perm:[1,0,3,2] row_mask:0xf bank_mask:0xf
	v_mov_b32_dpp v156, v147 quad_perm:[1,0,3,2] row_mask:0xf bank_mask:0xf
	v_cndmask_b32_e64 v33, v33, v146, s[42:43]
	v_cndmask_b32_e64 v32, v146, v32, s[42:43]
	v_cndmask_b32_e64 v35, v35, v156, s[42:43]
	v_cndmask_b32_e64 v34, v156, v34, s[42:43]
	v_cndmask_b32_e64 v145, v32, v34, s[44:45]
	v_cndmask_b32_e64 v147, v33, v35, s[44:45]
	s_nop 1
	v_mov_b32_dpp v146, v145 quad_perm:[2,3,0,1] row_mask:0xf bank_mask:0xf
	v_mov_b32_dpp v156, v147 quad_perm:[2,3,0,1] row_mask:0xf bank_mask:0xf
	v_cndmask_b32_e64 v34, v34, v146, s[44:45]
	v_cndmask_b32_e64 v32, v146, v32, s[44:45]
	v_cndmask_b32_e64 v35, v35, v156, s[44:45]
	v_cndmask_b32_e64 v33, v156, v33, s[44:45]
	global_store_dwordx4 v200, v[4:7], s[10:11]
	global_store_dwordx4 v201, v[8:11], s[10:11]
	global_store_dwordx4 v202, v[12:15], s[10:11]
	global_store_dwordx4 v203, v[16:19], s[10:11]
	global_store_dwordx4 v204, v[20:23], s[10:11]
	global_store_dwordx4 v205, v[24:27], s[10:11]
	global_store_dwordx4 v206, v[28:31], s[10:11]
	global_store_dwordx4 v207, v[32:35], s[10:11]
	s_add_u32 s10, s10, s34
	s_addc_u32 s11, s11, 0
	s_waitcnt vmcnt(12)
	global_load_dwordx4 v[4:7], v200, s[8:9]
	global_load_dwordx4 v[8:11], v201, s[8:9]
	global_load_dwordx4 v[12:15], v202, s[8:9]
	global_load_dwordx4 v[16:19], v203, s[8:9]
	global_load_dwordx4 v[20:23], v204, s[8:9]
	global_load_dwordx4 v[24:27], v205, s[8:9]
	global_load_dwordx4 v[28:31], v206, s[8:9]
	global_load_dwordx4 v[32:35], v207, s[8:9]
	s_add_u32 s8, s8, s34
	s_addc_u32 s9, s9, 0
	v_cndmask_b32_e64 v145, v36, v37, s[42:43]
	v_cndmask_b32_e64 v147, v38, v39, s[42:43]
	s_nop 1
	v_mov_b32_dpp v146, v145 quad_perm:[1,0,3,2] row_mask:0xf bank_mask:0xf
	v_mov_b32_dpp v156, v147 quad_perm:[1,0,3,2] row_mask:0xf bank_mask:0xf
	v_cndmask_b32_e64 v37, v37, v146, s[42:43]
	v_cndmask_b32_e64 v36, v146, v36, s[42:43]
	v_cndmask_b32_e64 v39, v39, v156, s[42:43]
	v_cndmask_b32_e64 v38, v156, v38, s[42:43]
	v_cndmask_b32_e64 v145, v36, v38, s[44:45]
	v_cndmask_b32_e64 v147, v37, v39, s[44:45]
	s_nop 1
	v_mov_b32_dpp v146, v145 quad_perm:[2,3,0,1] row_mask:0xf bank_mask:0xf
	v_mov_b32_dpp v156, v147 quad_perm:[2,3,0,1] row_mask:0xf bank_mask:0xf
	v_cndmask_b32_e64 v38, v38, v146, s[44:45]
	v_cndmask_b32_e64 v36, v146, v36, s[44:45]
	v_cndmask_b32_e64 v39, v39, v156, s[44:45]
	v_cndmask_b32_e64 v37, v156, v37, s[44:45]
	v_cndmask_b32_e64 v145, v40, v41, s[42:43]
	v_cndmask_b32_e64 v147, v42, v43, s[42:43]
	s_nop 1
	v_mov_b32_dpp v146, v145 quad_perm:[1,0,3,2] row_mask:0xf bank_mask:0xf
	v_mov_b32_dpp v156, v147 quad_perm:[1,0,3,2] row_mask:0xf bank_mask:0xf
	v_cndmask_b32_e64 v41, v41, v146, s[42:43]
	v_cndmask_b32_e64 v40, v146, v40, s[42:43]
	v_cndmask_b32_e64 v43, v43, v156, s[42:43]
	v_cndmask_b32_e64 v42, v156, v42, s[42:43]
	v_cndmask_b32_e64 v145, v40, v42, s[44:45]
	v_cndmask_b32_e64 v147, v41, v43, s[44:45]
	s_nop 1
	v_mov_b32_dpp v146, v145 quad_perm:[2,3,0,1] row_mask:0xf bank_mask:0xf
	v_mov_b32_dpp v156, v147 quad_perm:[2,3,0,1] row_mask:0xf bank_mask:0xf
	v_cndmask_b32_e64 v42, v42, v146, s[44:45]
	v_cndmask_b32_e64 v40, v146, v40, s[44:45]
	v_cndmask_b32_e64 v43, v43, v156, s[44:45]
	v_cndmask_b32_e64 v41, v156, v41, s[44:45]
	v_cndmask_b32_e64 v145, v44, v45, s[42:43]
	v_cndmask_b32_e64 v147, v46, v47, s[42:43]
	s_nop 1
	v_mov_b32_dpp v146, v145 quad_perm:[1,0,3,2] row_mask:0xf bank_mask:0xf
	v_mov_b32_dpp v156, v147 quad_perm:[1,0,3,2] row_mask:0xf bank_mask:0xf
	v_cndmask_b32_e64 v45, v45, v146, s[42:43]
	v_cndmask_b32_e64 v44, v146, v44, s[42:43]
	v_cndmask_b32_e64 v47, v47, v156, s[42:43]
	v_cndmask_b32_e64 v46, v156, v46, s[42:43]
	v_cndmask_b32_e64 v145, v44, v46, s[44:45]
	v_cndmask_b32_e64 v147, v45, v47, s[44:45]
	s_nop 1
	v_mov_b32_dpp v146, v145 quad_perm:[2,3,0,1] row_mask:0xf bank_mask:0xf
	v_mov_b32_dpp v156, v147 quad_perm:[2,3,0,1] row_mask:0xf bank_mask:0xf
; #define LAS __attribute__((address_space(3)))
; __device__ __forceinline__ unsigned pk2(float lo, float hi) { const f32x2_t_ v = {lo, hi}; return __builtin_bit_cast(unsigned, __builtin_convertvector(v, bf16x2_t_)); }
; __device__ __forceinline__ void hg_chunk(const LAS unsigned char* sl, f32x4 (&S)[8], float* Orow, int nvalid, int vs, int lane) {
;     const int r = lane & 15, q = lane >> 4;
;     const bf16x8 vfr = *(const LAS bf16x8*)(sl + 16384 + ((vs * 64 + lane) << 4));
;     f32x4 o0 = {0.f, 0.f, 0.f, 0.f}, o1 = {0.f, 0.f, 0.f, 0.f};
;     { const bf16x8 s0 = *(const LAS bf16x8*)(sl + 24576 + (lane << 4)), s1 = *(const LAS bf16x8*)(sl + 24576 + ((64 + lane) << 4));
;       o0 = __builtin_amdgcn_mfma_f32_16x16x32_bf16(s0, vfr, o0, 0, 0, 0); o1 = __builtin_amdgcn_mfma_f32_16x16x32_bf16(s1, vfr, o1, 0, 0, 0); }
; #pragma unroll
;     for (int m = 0; m < 4; ++m) {
;         v4u sw; sw.x = pk2(S[2 * m][0], S[2 * m][1]); sw.y = pk2(S[2 * m][2], S[2 * m][3]); sw.z = pk2(S[2 * m + 1][0], S[2 * m + 1][1]); sw.w = pk2(S[2 * m + 1][2], S[2 * m + 1][3]);
;         const bf16x8 sb = __builtin_bit_cast(bf16x8, sw);
;         const bf16x8 a0 = *(const LAS bf16x8*)(sl + ((m * 64 + lane) << 4)), a1 = *(const LAS bf16x8*)(sl + (((4 + m) * 64 + lane) << 4));
;         o0 = __builtin_amdgcn_mfma_f32_16x16x32_bf16(a0, sb, o0, 0, 0, 0); o1 = __builtin_amdgcn_mfma_f32_16x16x32_bf16(a1, sb, o1, 0, 0, 0);
;     }
; #pragma unroll
;     for (int i = 0; i < 4; ++i) { const int c0 = 4 * q + i;
;         if (c0 < nvalid) Orow[(size_t)c0 * DA + 16 * vs + r] = o0[i];
;         if (c0 + 16 < nvalid) Orow[(size_t)(c0 + 16) * DA + 16 * vs + r] = o1[i]; }
; #pragma unroll
;     for (int kb = 0; kb < 8; ++kb) { const f32x4 d = *(const LAS f32x4*)(sl + 26624 + ((16 * kb + 4 * q) << 2));
;         const bf16x8 ke = *(const LAS bf16x8*)(sl + 8192 + ((kb * 64 + lane) << 4));
;         S[kb] = __builtin_amdgcn_mfma_f32_16x16x32_bf16(ke, vfr, S[kb] * d, 0, 0, 0); }
	v_cndmask_b32_e64 v46, v46, v146, s[44:45]
	v_cndmask_b32_e64 v44, v146, v44, s[44:45]
	v_cndmask_b32_e64 v47, v47, v156, s[44:45]
	v_cndmask_b32_e64 v45, v156, v45, s[44:45]
	v_cndmask_b32_e64 v145, v48, v49, s[42:43]
	v_cndmask_b32_e64 v147, v50, v51, s[42:43]
	s_nop 1
	v_mov_b32_dpp v146, v145 quad_perm:[1,0,3,2] row_mask:0xf bank_mask:0xf
	v_mov_b32_dpp v156, v147 quad_perm:[1,0,3,2] row_mask:0xf bank_mask:0xf
	v_cndmask_b32_e64 v49, v49, v146, s[42:43]
	v_cndmask_b32_e64 v48, v146, v48, s[42:43]
	v_cndmask_b32_e64 v51, v51, v156, s[42:43]
	v_cndmask_b32_e64 v50, v156, v50, s[42:43]
	v_cndmask_b32_e64 v145, v48, v50, s[44:45]
	v_cndmask_b32_e64 v147, v49, v51, s[44:45]
	s_nop 1
	v_mov_b32_dpp v146, v145 quad_perm:[2,3,0,1] row_mask:0xf bank_mask:0xf
	v_mov_b32_dpp v156, v147 quad_perm:[2,3,0,1] row_mask:0xf bank_mask:0xf
	v_cndmask_b32_e64 v50, v50, v146, s[44:45]
	v_cndmask_b32_e64 v48, v146, v48, s[44:45]
	v_cndmask_b32_e64 v51, v51, v156, s[44:45]
	v_cndmask_b32_e64 v49, v156, v49, s[44:45]
	v_cndmask_b32_e64 v145, v52, v53, s[42:43]
	v_cndmask_b32_e64 v147, v54, v55, s[42:43]
	s_nop 1
	v_mov_b32_dpp v146, v145 quad_perm:[1,0,3,2] row_mask:0xf bank_mask:0xf
	v_mov_b32_dpp v156, v147 quad_perm:[1,0,3,2] row_mask:0xf bank_mask:0xf
	v_cndmask_b32_e64 v53, v53, v146, s[42:43]
	v_cndmask_b32_e64 v52, v146, v52, s[42:43]
	v_cndmask_b32_e64 v55, v55, v156, s[42:43]
	v_cndmask_b32_e64 v54, v156, v54, s[42:43]
	v_cndmask_b32_e64 v145, v52, v54, s[44:45]
	v_cndmask_b32_e64 v147, v53, v55, s[44:45]
	s_nop 1
	v_mov_b32_dpp v146, v145 quad_perm:[2,3,0,1] row_mask:0xf bank_mask:0xf
	v_mov_b32_dpp v156, v147 quad_perm:[2,3,0,1] row_mask:0xf bank_mask:0xf
	v_cndmask_b32_e64 v54, v54, v146, s[44:45]
	v_cndmask_b32_e64 v52, v146, v52, s[44:45]
	v_cndmask_b32_e64 v55, v55, v156, s[44:45]
	v_cndmask_b32_e64 v53, v156, v53, s[44:45]
	v_cndmask_b32_e64 v145, v56, v57, s[42:43]
	v_cndmask_b32_e64 v147, v58, v59, s[42:43]
	s_nop 1
	v_mov_b32_dpp v146, v145 quad_perm:[1,0,3,2] row_mask:0xf bank_mask:0xf
	v_mov_b32_dpp v156, v147 quad_perm:[1,0,3,2] row_mask:0xf bank_mask:0xf
	v_cndmask_b32_e64 v57, v57, v146, s[42:43]
	v_cndmask_b32_e64 v56, v146, v56, s[42:43]
	v_cndmask_b32_e64 v59, v59, v156, s[42:43]
	v_cndmask_b32_e64 v58, v156, v58, s[42:43]
	v_cndmask_b32_e64 v145, v56, v58, s[44:45]
	v_cndmask_b32_e64 v147, v57, v59, s[44:45]
	s_nop 1
	v_mov_b32_dpp v146, v145 quad_perm:[2,3,0,1] row_mask:0xf bank_mask:0xf
	v_mov_b32_dpp v156, v147 quad_perm:[2,3,0,1] row_mask:0xf bank_mask:0xf
	v_cndmask_b32_e64 v58, v58, v146, s[44:45]
	v_cndmask_b32_e64 v56, v146, v56, s[44:45]
	v_cndmask_b32_e64 v59, v59, v156, s[44:45]
	v_cndmask_b32_e64 v57, v156, v57, s[44:45]
	v_cndmask_b32_e64 v145, v60, v61, s[42:43]
	v_cndmask_b32_e64 v147, v62, v63, s[42:43]
	s_nop 1
	v_mov_b32_dpp v146, v145 quad_perm:[1,0,3,2] row_mask:0xf bank_mask:0xf
	v_mov_b32_dpp v156, v147 quad_perm:[1,0,3,2] row_mask:0xf bank_mask:0xf
	v_cndmask_b32_e64 v61, v61, v146, s[42:43]
	v_cndmask_b32_e64 v60, v146, v60, s[42:43]
	v_cndmask_b32_e64 v63, v63, v156, s[42:43]
	v_cndmask_b32_e64 v62, v156, v62, s[42:43]
	v_cndmask_b32_e64 v145, v60, v62, s[44:45]
	v_cndmask_b32_e64 v147, v61, v63, s[44:45]
	s_nop 1
	v_mov_b32_dpp v146, v145 quad_perm:[2,3,0,1] row_mask:0xf bank_mask:0xf
	v_mov_b32_dpp v156, v147 quad_perm:[2,3,0,1] row_mask:0xf bank_mask:0xf
	v_cndmask_b32_e64 v62, v62, v146, s[44:45]
	v_cndmask_b32_e64 v60, v146, v60, s[44:45]
	v_cndmask_b32_e64 v63, v63, v156, s[44:45]
	v_cndmask_b32_e64 v61, v156, v61, s[44:45]
	v_cndmask_b32_e64 v145, v64, v65, s[42:43]
	v_cndmask_b32_e64 v147, v66, v67, s[42:43]
	s_nop 1
	v_mov_b32_dpp v146, v145 quad_perm:[1,0,3,2] row_mask:0xf bank_mask:0xf
	v_mov_b32_dpp v156, v147 quad_perm:[1,0,3,2] row_mask:0xf bank_mask:0xf
	v_cndmask_b32_e64 v65, v65, v146, s[42:43]
	v_cndmask_b32_e64 v64, v146, v64, s[42:43]
	v_cndmask_b32_e64 v67, v67, v156, s[42:43]
	v_cndmask_b32_e64 v66, v156, v66, s[42:43]
	v_cndmask_b32_e64 v145, v64, v66, s[44:45]
	v_cndmask_b32_e64 v147, v65, v67, s[44:45]
	s_nop 1
	v_mov_b32_dpp v146, v145 quad_perm:[2,3,0,1] row_mask:0xf bank_mask:0xf
	v_mov_b32_dpp v156, v147 quad_perm:[2,3,0,1] row_mask:0xf bank_mask:0xf
	v_cndmask_b32_e64 v66, v66, v146, s[44:45]
	v_cndmask_b32_e64 v64, v146, v64, s[44:45]
	v_cndmask_b32_e64 v67, v67, v156, s[44:45]
	v_cndmask_b32_e64 v65, v156, v65, s[44:45]
	v_add_u32_e32 v1, 0x6c00, v142
	v_add_u32_e32 v2, 0x6c00, v143
	v_add_u32_e32 v3, 0x6c00, v144
	ds_read_b128 v[164:167], v3 offset:26624
	ds_read_b128 v[168:171], v3 offset:26688
	ds_read_b128 v[172:175], v3 offset:26752
	ds_read_b128 v[176:179], v3 offset:26816
	ds_read_b128 v[180:183], v3 offset:26880
	ds_read_b128 v[184:187], v3 offset:26944
	ds_read_b128 v[148:151], v3 offset:27008
	ds_read_b128 v[152:155], v3 offset:27072
	ds_read_b128 v[84:87], v2 offset:16384
	ds_read_b128 v[88:91], v1 offset:24576
	ds_read_b128 v[92:95], v1 offset:0
	ds_read_b128 v[96:99], v1 offset:1024
	ds_read_b128 v[100:103], v1 offset:2048
	ds_read_b128 v[104:107], v1 offset:3072
	v_cvt_pk_bf16_f32 v68, v36, v37
	v_cvt_pk_bf16_f32 v69, v38, v39
	v_cvt_pk_bf16_f32 v70, v40, v41
	v_cvt_pk_bf16_f32 v71, v42, v43
	v_cvt_pk_bf16_f32 v72, v44, v45
	v_cvt_pk_bf16_f32 v73, v46, v47
	v_cvt_pk_bf16_f32 v74, v48, v49
	v_cvt_pk_bf16_f32 v75, v50, v51
	v_cvt_pk_bf16_f32 v76, v52, v53
	v_cvt_pk_bf16_f32 v77, v54, v55
	v_cvt_pk_bf16_f32 v78, v56, v57
	v_cvt_pk_bf16_f32 v79, v58, v59
	v_cvt_pk_bf16_f32 v80, v60, v61
	v_cvt_pk_bf16_f32 v81, v62, v63
	v_cvt_pk_bf16_f32 v82, v64, v65
	v_cvt_pk_bf16_f32 v83, v66, v67
	s_waitcnt lgkmcnt(6)
; #define LAS __attribute__((address_space(3)))
; __device__ __forceinline__ unsigned pk2(float lo, float hi) { const f32x2_t_ v = {lo, hi}; return __builtin_bit_cast(unsigned, __builtin_convertvector(v, bf16x2_t_)); }
; __device__ __forceinline__ void hg_chunk(const LAS unsigned char* sl, f32x4 (&S)[8], float* Orow, int nvalid, int vs, int lane) {
;     const int r = lane & 15, q = lane >> 4;
;     const bf16x8 vfr = *(const LAS bf16x8*)(sl + 16384 + ((vs * 64 + lane) << 4));
;     f32x4 o0 = {0.f, 0.f, 0.f, 0.f}, o1 = {0.f, 0.f, 0.f, 0.f};
;     { const bf16x8 s0 = *(const LAS bf16x8*)(sl + 24576 + (lane << 4)), s1 = *(const LAS bf16x8*)(sl + 24576 + ((64 + lane) << 4));
;       o0 = __builtin_amdgcn_mfma_f32_16x16x32_bf16(s0, vfr, o0, 0, 0, 0); o1 = __builtin_amdgcn_mfma_f32_16x16x32_bf16(s1, vfr, o1, 0, 0, 0); }
; #pragma unroll
;     for (int m = 0; m < 4; ++m) {
;         v4u sw; sw.x = pk2(S[2 * m][0], S[2 * m][1]); sw.y = pk2(S[2 * m][2], S[2 * m][3]); sw.z = pk2(S[2 * m + 1][0], S[2 * m + 1][1]); sw.w = pk2(S[2 * m + 1][2], S[2 * m + 1][3]);
;         const bf16x8 sb = __builtin_bit_cast(bf16x8, sw);
;         const bf16x8 a0 = *(const LAS bf16x8*)(sl + ((m * 64 + lane) << 4)), a1 = *(const LAS bf16x8*)(sl + (((4 + m) * 64 + lane) << 4));
;         o0 = __builtin_amdgcn_mfma_f32_16x16x32_bf16(a0, sb, o0, 0, 0, 0); o1 = __builtin_amdgcn_mfma_f32_16x16x32_bf16(a1, sb, o1, 0, 0, 0);
;     }
; #pragma unroll
;     for (int i = 0; i < 4; ++i) { const int c0 = 4 * q + i;
;         if (c0 < nvalid) Orow[(size_t)c0 * DA + 16 * vs + r] = o0[i];
;         if (c0 + 16 < nvalid) Orow[(size_t)(c0 + 16) * DA + 16 * vs + r] = o1[i]; }
; #pragma unroll
;     for (int kb = 0; kb < 8; ++kb) { const f32x4 d = *(const LAS f32x4*)(sl + 26624 + ((16 * kb + 4 * q) << 2));
;         const bf16x8 ke = *(const LAS bf16x8*)(sl + 8192 + ((kb * 64 + lane) << 4));
;         S[kb] = __builtin_amdgcn_mfma_f32_16x16x32_bf16(ke, vfr, S[kb] * d, 0, 0, 0); }
	v_pk_mul_f32 v[36:37], v[36:37], v[164:165]
	v_pk_mul_f32 v[38:39], v[38:39], v[166:167]
	v_pk_mul_f32 v[40:41], v[40:41], v[168:169]
	v_pk_mul_f32 v[42:43], v[42:43], v[170:171]
	v_pk_mul_f32 v[44:45], v[44:45], v[172:173]
	v_pk_mul_f32 v[46:47], v[46:47], v[174:175]
	v_pk_mul_f32 v[48:49], v[48:49], v[176:177]
	v_pk_mul_f32 v[50:51], v[50:51], v[178:179]
	v_pk_mul_f32 v[52:53], v[52:53], v[180:181]
	v_pk_mul_f32 v[54:55], v[54:55], v[182:183]
	v_pk_mul_f32 v[56:57], v[56:57], v[184:185]
	v_pk_mul_f32 v[58:59], v[58:59], v[186:187]
	v_pk_mul_f32 v[60:61], v[60:61], v[148:149]
	v_pk_mul_f32 v[62:63], v[62:63], v[150:151]
	v_pk_mul_f32 v[64:65], v[64:65], v[152:153]
	v_pk_mul_f32 v[66:67], v[66:67], v[154:155]
	ds_read_b128 v[108:111], v1 offset:8192
	ds_read_b128 v[112:115], v1 offset:9216
	ds_read_b128 v[116:119], v1 offset:10240
	ds_read_b128 v[120:123], v1 offset:11264
	ds_read_b128 v[124:127], v1 offset:12288
	ds_read_b128 v[128:131], v1 offset:13312
	ds_read_b128 v[132:135], v1 offset:14336
	ds_read_b128 v[136:139], v1 offset:15360
	s_waitcnt lgkmcnt(12)
	v_mfma_f32_16x16x32_bf16 v[196:199], v[88:91], v[84:87], 0
	s_waitcnt lgkmcnt(11)
	v_mfma_f32_16x16x32_bf16 v[196:199], v[92:95], v[68:71], v[196:199]
	s_waitcnt lgkmcnt(10)
	v_mfma_f32_16x16x32_bf16 v[196:199], v[96:99], v[72:75], v[196:199]
	s_waitcnt lgkmcnt(9)
	v_mfma_f32_16x16x32_bf16 v[196:199], v[100:103], v[76:79], v[196:199]
	s_waitcnt lgkmcnt(8)
	v_mfma_f32_16x16x32_bf16 v[196:199], v[104:107], v[80:83], v[196:199]
	s_waitcnt lgkmcnt(7)
	v_mfma_f32_16x16x32_bf16 v[36:39], v[108:111], v[84:87], v[36:39]
	s_waitcnt lgkmcnt(6)
	v_mfma_f32_16x16x32_bf16 v[40:43], v[112:115], v[84:87], v[40:43]
	s_waitcnt lgkmcnt(5)
	v_mfma_f32_16x16x32_bf16 v[44:47], v[116:119], v[84:87], v[44:47]
	s_waitcnt lgkmcnt(4)
	v_mfma_f32_16x16x32_bf16 v[48:51], v[120:123], v[84:87], v[48:51]
	s_waitcnt lgkmcnt(3)
	v_mfma_f32_16x16x32_bf16 v[52:55], v[124:127], v[84:87], v[52:55]
	s_waitcnt lgkmcnt(2)
	v_mfma_f32_16x16x32_bf16 v[56:59], v[128:131], v[84:87], v[56:59]
	s_waitcnt lgkmcnt(1)
	v_mfma_f32_16x16x32_bf16 v[60:63], v[132:135], v[84:87], v[60:63]
	s_waitcnt lgkmcnt(0)
	v_mfma_f32_16x16x32_bf16 v[64:67], v[136:139], v[84:87], v[64:67]
	s_mov_b32 exec_hi, 0
	global_store_dword v208, v196, s[12:13]
	global_store_dword v208, v197, s[12:13] offset:2048
	global_store_dword v209, v198, s[12:13]
	global_store_dword v209, v199, s[12:13] offset:2048
	s_mov_b64 exec, -1
	s_add_u32 s12, s12, 0x80000
	s_addc_u32 s13, s13, 0
	s_nop 7
	v_cndmask_b32_e64 v145, v36, v37, s[42:43]
	v_cndmask_b32_e64 v147, v38, v39, s[42:43]
	s_nop 1
	v_mov_b32_dpp v146, v145 quad_perm:[1,0,3,2] row_mask:0xf bank_mask:0xf
	v_mov_b32_dpp v156, v147 quad_perm:[1,0,3,2] row_mask:0xf bank_mask:0xf
	v_cndmask_b32_e64 v37, v37, v146, s[42:43]
	v_cndmask_b32_e64 v36, v146, v36, s[42:43]
	v_cndmask_b32_e64 v39, v39, v156, s[42:43]
	v_cndmask_b32_e64 v38, v156, v38, s[42:43]
	v_cndmask_b32_e64 v145, v36, v38, s[44:45]
	v_cndmask_b32_e64 v147, v37, v39, s[44:45]
	s_nop 1
	v_mov_b32_dpp v146, v145 quad_perm:[2,3,0,1] row_mask:0xf bank_mask:0xf
	v_mov_b32_dpp v156, v147 quad_perm:[2,3,0,1] row_mask:0xf bank_mask:0xf
	v_cndmask_b32_e64 v38, v38, v146, s[44:45]
	v_cndmask_b32_e64 v36, v146, v36, s[44:45]
	v_cndmask_b32_e64 v39, v39, v156, s[44:45]
	v_cndmask_b32_e64 v37, v156, v37, s[44:45]
	v_cndmask_b32_e64 v145, v40, v41, s[42:43]
	v_cndmask_b32_e64 v147, v42, v43, s[42:43]
	s_nop 1
	v_mov_b32_dpp v146, v145 quad_perm:[1,0,3,2] row_mask:0xf bank_mask:0xf
	v_mov_b32_dpp v156, v147 quad_perm:[1,0,3,2] row_mask:0xf bank_mask:0xf
	v_cndmask_b32_e64 v41, v41, v146, s[42:43]
	v_cndmask_b32_e64 v40, v146, v40, s[42:43]
	v_cndmask_b32_e64 v43, v43, v156, s[42:43]
	v_cndmask_b32_e64 v42, v156, v42, s[42:43]
	v_cndmask_b32_e64 v145, v40, v42, s[44:45]
	v_cndmask_b32_e64 v147, v41, v43, s[44:45]
	s_nop 1
	v_mov_b32_dpp v146, v145 quad_perm:[2,3,0,1] row_mask:0xf bank_mask:0xf
	v_mov_b32_dpp v156, v147 quad_perm:[2,3,0,1] row_mask:0xf bank_mask:0xf
	v_cndmask_b32_e64 v42, v42, v146, s[44:45]
	v_cndmask_b32_e64 v40, v146, v40, s[44:45]
	v_cndmask_b32_e64 v43, v43, v156, s[44:45]
	v_cndmask_b32_e64 v41, v156, v41, s[44:45]
	v_cndmask_b32_e64 v145, v44, v45, s[42:43]
	v_cndmask_b32_e64 v147, v46, v47, s[42:43]
	s_nop 1
	v_mov_b32_dpp v146, v145 quad_perm:[1,0,3,2] row_mask:0xf bank_mask:0xf
	v_mov_b32_dpp v156, v147 quad_perm:[1,0,3,2] row_mask:0xf bank_mask:0xf
	v_cndmask_b32_e64 v45, v45, v146, s[42:43]
	v_cndmask_b32_e64 v44, v146, v44, s[42:43]
	v_cndmask_b32_e64 v47, v47, v156, s[42:43]
	v_cndmask_b32_e64 v46, v156, v46, s[42:43]
	v_cndmask_b32_e64 v145, v44, v46, s[44:45]
	v_cndmask_b32_e64 v147, v45, v47, s[44:45]
	s_nop 1
	v_mov_b32_dpp v146, v145 quad_perm:[2,3,0,1] row_mask:0xf bank_mask:0xf
	v_mov_b32_dpp v156, v147 quad_perm:[2,3,0,1] row_mask:0xf bank_mask:0xf
	v_cndmask_b32_e64 v46, v46, v146, s[44:45]
	v_cndmask_b32_e64 v44, v146, v44, s[44:45]
	v_cndmask_b32_e64 v47, v47, v156, s[44:45]
	v_cndmask_b32_e64 v45, v156, v45, s[44:45]
	v_cndmask_b32_e64 v145, v48, v49, s[42:43]
	v_cndmask_b32_e64 v147, v50, v51, s[42:43]
	s_nop 1
	v_mov_b32_dpp v146, v145 quad_perm:[1,0,3,2] row_mask:0xf bank_mask:0xf
	v_mov_b32_dpp v156, v147 quad_perm:[1,0,3,2] row_mask:0xf bank_mask:0xf
	v_cndmask_b32_e64 v49, v49, v146, s[42:43]
	v_cndmask_b32_e64 v48, v146, v48, s[42:43]
	v_cndmask_b32_e64 v51, v51, v156, s[42:43]
	v_cndmask_b32_e64 v50, v156, v50, s[42:43]
	v_cndmask_b32_e64 v145, v48, v50, s[44:45]
	v_cndmask_b32_e64 v147, v49, v51, s[44:45]
	s_nop 1
	v_mov_b32_dpp v146, v145 quad_perm:[2,3,0,1] row_mask:0xf bank_mask:0xf
; __device__ __forceinline__ void hg_seq(const Frame& F, unsigned char* ws, const float* s0, float* sout, float* Og, int seq, bool sample, int vs_base, int nvs) {
;     ...
;     if (sample && active) {
; #pragma unroll
;         for (int kb = 0; kb < 8; ++kb)
; #pragma unroll
;             for (int i = 0; i < 4; ++i) S[kb][i] = s0[((size_t)seq * 128 + 16 * kb + 4 * q + i) * 128 + 16 * vs + r];
;     } else {
;     ...
;     if (active) {
; #pragma unroll
;     for (int kb = 0; kb < 8; ++kb)
; #pragma unroll
;         for (int i = 0; i < 4; ++i) sout[((size_t)seq * 128 + 16 * kb + 4 * q + i) * 128 + 16 * vs + r] = S[kb][i];
;     }
	v_mov_b32_dpp v156, v147 quad_perm:[2,3,0,1] row_mask:0xf bank_mask:0xf
	v_cndmask_b32_e64 v50, v50, v146, s[44:45]
	v_cndmask_b32_e64 v48, v146, v48, s[44:45]
	v_cndmask_b32_e64 v51, v51, v156, s[44:45]
	v_cndmask_b32_e64 v49, v156, v49, s[44:45]
	v_cndmask_b32_e64 v145, v52, v53, s[42:43]
	v_cndmask_b32_e64 v147, v54, v55, s[42:43]
	s_nop 1
	v_mov_b32_dpp v146, v145 quad_perm:[1,0,3,2] row_mask:0xf bank_mask:0xf
	v_mov_b32_dpp v156, v147 quad_perm:[1,0,3,2] row_mask:0xf bank_mask:0xf
	v_cndmask_b32_e64 v53, v53, v146, s[42:43]
	v_cndmask_b32_e64 v52, v146, v52, s[42:43]
	v_cndmask_b32_e64 v55, v55, v156, s[42:43]
	v_cndmask_b32_e64 v54, v156, v54, s[42:43]
	v_cndmask_b32_e64 v145, v52, v54, s[44:45]
	v_cndmask_b32_e64 v147, v53, v55, s[44:45]
	s_nop 1
	v_mov_b32_dpp v146, v145 quad_perm:[2,3,0,1] row_mask:0xf bank_mask:0xf
	v_mov_b32_dpp v156, v147 quad_perm:[2,3,0,1] row_mask:0xf bank_mask:0xf
	v_cndmask_b32_e64 v54, v54, v146, s[44:45]
	v_cndmask_b32_e64 v52, v146, v52, s[44:45]
	v_cndmask_b32_e64 v55, v55, v156, s[44:45]
	v_cndmask_b32_e64 v53, v156, v53, s[44:45]
	v_cndmask_b32_e64 v145, v56, v57, s[42:43]
	v_cndmask_b32_e64 v147, v58, v59, s[42:43]
	s_nop 1
	v_mov_b32_dpp v146, v145 quad_perm:[1,0,3,2] row_mask:0xf bank_mask:0xf
	v_mov_b32_dpp v156, v147 quad_perm:[1,0,3,2] row_mask:0xf bank_mask:0xf
	v_cndmask_b32_e64 v57, v57, v146, s[42:43]
	v_cndmask_b32_e64 v56, v146, v56, s[42:43]
	v_cndmask_b32_e64 v59, v59, v156, s[42:43]
	v_cndmask_b32_e64 v58, v156, v58, s[42:43]
	v_cndmask_b32_e64 v145, v56, v58, s[44:45]
	v_cndmask_b32_e64 v147, v57, v59, s[44:45]
	s_nop 1
	v_mov_b32_dpp v146, v145 quad_perm:[2,3,0,1] row_mask:0xf bank_mask:0xf
	v_mov_b32_dpp v156, v147 quad_perm:[2,3,0,1] row_mask:0xf bank_mask:0xf
	v_cndmask_b32_e64 v58, v58, v146, s[44:45]
	v_cndmask_b32_e64 v56, v146, v56, s[44:45]
	v_cndmask_b32_e64 v59, v59, v156, s[44:45]
	v_cndmask_b32_e64 v57, v156, v57, s[44:45]
	v_cndmask_b32_e64 v145, v60, v61, s[42:43]
	v_cndmask_b32_e64 v147, v62, v63, s[42:43]
	s_nop 1
	v_mov_b32_dpp v146, v145 quad_perm:[1,0,3,2] row_mask:0xf bank_mask:0xf
	v_mov_b32_dpp v156, v147 quad_perm:[1,0,3,2] row_mask:0xf bank_mask:0xf
	v_cndmask_b32_e64 v61, v61, v146, s[42:43]
	v_cndmask_b32_e64 v60, v146, v60, s[42:43]
	v_cndmask_b32_e64 v63, v63, v156, s[42:43]
	v_cndmask_b32_e64 v62, v156, v62, s[42:43]
	v_cndmask_b32_e64 v145, v60, v62, s[44:45]
	v_cndmask_b32_e64 v147, v61, v63, s[44:45]
	s_nop 1
	v_mov_b32_dpp v146, v145 quad_perm:[2,3,0,1] row_mask:0xf bank_mask:0xf
	v_mov_b32_dpp v156, v147 quad_perm:[2,3,0,1] row_mask:0xf bank_mask:0xf
	v_cndmask_b32_e64 v62, v62, v146, s[44:45]
	v_cndmask_b32_e64 v60, v146, v60, s[44:45]
	v_cndmask_b32_e64 v63, v63, v156, s[44:45]
	v_cndmask_b32_e64 v61, v156, v61, s[44:45]
	v_cndmask_b32_e64 v145, v64, v65, s[42:43]
	v_cndmask_b32_e64 v147, v66, v67, s[42:43]
	s_nop 1
	v_mov_b32_dpp v146, v145 quad_perm:[1,0,3,2] row_mask:0xf bank_mask:0xf
	v_mov_b32_dpp v156, v147 quad_perm:[1,0,3,2] row_mask:0xf bank_mask:0xf
	v_cndmask_b32_e64 v65, v65, v146, s[42:43]
	v_cndmask_b32_e64 v64, v146, v64, s[42:43]
	v_cndmask_b32_e64 v67, v67, v156, s[42:43]
	v_cndmask_b32_e64 v66, v156, v66, s[42:43]
	v_cndmask_b32_e64 v145, v64, v66, s[44:45]
	v_cndmask_b32_e64 v147, v65, v67, s[44:45]
	s_nop 1
	v_mov_b32_dpp v146, v145 quad_perm:[2,3,0,1] row_mask:0xf bank_mask:0xf
	v_mov_b32_dpp v156, v147 quad_perm:[2,3,0,1] row_mask:0xf bank_mask:0xf
	v_cndmask_b32_e64 v66, v66, v146, s[44:45]
	v_cndmask_b32_e64 v64, v146, v64, s[44:45]
	v_cndmask_b32_e64 v67, v67, v156, s[44:45]
	v_cndmask_b32_e64 v65, v156, v65, s[44:45]
	global_store_dwordx4 v200, v[36:39], s[10:11]
	global_store_dwordx4 v201, v[40:43], s[10:11]
	global_store_dwordx4 v202, v[44:47], s[10:11]
	global_store_dwordx4 v203, v[48:51], s[10:11]
	global_store_dwordx4 v204, v[52:55], s[10:11]
	global_store_dwordx4 v205, v[56:59], s[10:11]
	global_store_dwordx4 v206, v[60:63], s[10:11]
	global_store_dwordx4 v207, v[64:67], s[10:11]
	s_add_u32 s10, s10, s34
	s_addc_u32 s11, s11, 0
	s_waitcnt vmcnt(12)
	v_cndmask_b32_e64 v145, v4, v5, s[42:43]
	v_cndmask_b32_e64 v147, v6, v7, s[42:43]
	s_nop 1
	v_mov_b32_dpp v146, v145 quad_perm:[1,0,3,2] row_mask:0xf bank_mask:0xf
	v_mov_b32_dpp v156, v147 quad_perm:[1,0,3,2] row_mask:0xf bank_mask:0xf
	v_cndmask_b32_e64 v5, v5, v146, s[42:43]
	v_cndmask_b32_e64 v4, v146, v4, s[42:43]
	v_cndmask_b32_e64 v7, v7, v156, s[42:43]
	v_cndmask_b32_e64 v6, v156, v6, s[42:43]
	v_cndmask_b32_e64 v145, v4, v6, s[44:45]
	v_cndmask_b32_e64 v147, v5, v7, s[44:45]
	s_nop 1
	v_mov_b32_dpp v146, v145 quad_perm:[2,3,0,1] row_mask:0xf bank_mask:0xf
	v_mov_b32_dpp v156, v147 quad_perm:[2,3,0,1] row_mask:0xf bank_mask:0xf
	v_cndmask_b32_e64 v6, v6, v146, s[44:45]
	v_cndmask_b32_e64 v4, v146, v4, s[44:45]
	v_cndmask_b32_e64 v7, v7, v156, s[44:45]
	v_cndmask_b32_e64 v5, v156, v5, s[44:45]
	v_cndmask_b32_e64 v145, v8, v9, s[42:43]
	v_cndmask_b32_e64 v147, v10, v11, s[42:43]
	s_nop 1
	v_mov_b32_dpp v146, v145 quad_perm:[1,0,3,2] row_mask:0xf bank_mask:0xf
	v_mov_b32_dpp v156, v147 quad_perm:[1,0,3,2] row_mask:0xf bank_mask:0xf
	v_cndmask_b32_e64 v9, v9, v146, s[42:43]
	v_cndmask_b32_e64 v8, v146, v8, s[42:43]
	v_cndmask_b32_e64 v11, v11, v156, s[42:43]
	v_cndmask_b32_e64 v10, v156, v10, s[42:43]
	v_cndmask_b32_e64 v145, v8, v10, s[44:45]
	v_cndmask_b32_e64 v147, v9, v11, s[44:45]
	s_nop 1
	v_mov_b32_dpp v146, v145 quad_perm:[2,3,0,1] row_mask:0xf bank_mask:0xf
	v_mov_b32_dpp v156, v147 quad_perm:[2,3,0,1] row_mask:0xf bank_mask:0xf
	v_cndmask_b32_e64 v10, v10, v146, s[44:45]
	v_cndmask_b32_e64 v8, v146, v8, s[44:45]
	v_cndmask_b32_e64 v11, v11, v156, s[44:45]
; #define LAS __attribute__((address_space(3)))
; __device__ __forceinline__ unsigned pk2(float lo, float hi) { const f32x2_t_ v = {lo, hi}; return __builtin_bit_cast(unsigned, __builtin_convertvector(v, bf16x2_t_)); }
; __device__ __forceinline__ void hg_chunk(const LAS unsigned char* sl, f32x4 (&S)[8], float* Orow, int nvalid, int vs, int lane) {
;     const int r = lane & 15, q = lane >> 4;
;     const bf16x8 vfr = *(const LAS bf16x8*)(sl + 16384 + ((vs * 64 + lane) << 4));
;     f32x4 o0 = {0.f, 0.f, 0.f, 0.f}, o1 = {0.f, 0.f, 0.f, 0.f};
;     { const bf16x8 s0 = *(const LAS bf16x8*)(sl + 24576 + (lane << 4)), s1 = *(const LAS bf16x8*)(sl + 24576 + ((64 + lane) << 4));
;       o0 = __builtin_amdgcn_mfma_f32_16x16x32_bf16(s0, vfr, o0, 0, 0, 0); o1 = __builtin_amdgcn_mfma_f32_16x16x32_bf16(s1, vfr, o1, 0, 0, 0); }
; #pragma unroll
;     for (int m = 0; m < 4; ++m) {
;         v4u sw; sw.x = pk2(S[2 * m][0], S[2 * m][1]); sw.y = pk2(S[2 * m][2], S[2 * m][3]); sw.z = pk2(S[2 * m + 1][0], S[2 * m + 1][1]); sw.w = pk2(S[2 * m + 1][2], S[2 * m + 1][3]);
;         const bf16x8 sb = __builtin_bit_cast(bf16x8, sw);
;         const bf16x8 a0 = *(const LAS bf16x8*)(sl + ((m * 64 + lane) << 4)), a1 = *(const LAS bf16x8*)(sl + (((4 + m) * 64 + lane) << 4));
; __device__ __forceinline__ void hg_seq(const Frame& F, unsigned char* ws, const float* s0, float* sout, float* Og, int seq, bool sample, int vs_base, int nvs) {
;     ...
;     if (sample && active) {
; #pragma unroll
;         for (int kb = 0; kb < 8; ++kb)
; #pragma unroll
;             for (int i = 0; i < 4; ++i) S[kb][i] = s0[((size_t)seq * 128 + 16 * kb + 4 * q + i) * 128 + 16 * vs + r];
;     } else {
	v_cndmask_b32_e64 v9, v156, v9, s[44:45]
	v_cndmask_b32_e64 v145, v12, v13, s[42:43]
	v_cndmask_b32_e64 v147, v14, v15, s[42:43]
	s_nop 1
	v_mov_b32_dpp v146, v145 quad_perm:[1,0,3,2] row_mask:0xf bank_mask:0xf
	v_mov_b32_dpp v156, v147 quad_perm:[1,0,3,2] row_mask:0xf bank_mask:0xf
	v_cndmask_b32_e64 v13, v13, v146, s[42:43]
	v_cndmask_b32_e64 v12, v146, v12, s[42:43]
	v_cndmask_b32_e64 v15, v15, v156, s[42:43]
	v_cndmask_b32_e64 v14, v156, v14, s[42:43]
	v_cndmask_b32_e64 v145, v12, v14, s[44:45]
	v_cndmask_b32_e64 v147, v13, v15, s[44:45]
	s_nop 1
	v_mov_b32_dpp v146, v145 quad_perm:[2,3,0,1] row_mask:0xf bank_mask:0xf
	v_mov_b32_dpp v156, v147 quad_perm:[2,3,0,1] row_mask:0xf bank_mask:0xf
	v_cndmask_b32_e64 v14, v14, v146, s[44:45]
	v_cndmask_b32_e64 v12, v146, v12, s[44:45]
	v_cndmask_b32_e64 v15, v15, v156, s[44:45]
	v_cndmask_b32_e64 v13, v156, v13, s[44:45]
	v_cndmask_b32_e64 v145, v16, v17, s[42:43]
	v_cndmask_b32_e64 v147, v18, v19, s[42:43]
	s_nop 1
	v_mov_b32_dpp v146, v145 quad_perm:[1,0,3,2] row_mask:0xf bank_mask:0xf
	v_mov_b32_dpp v156, v147 quad_perm:[1,0,3,2] row_mask:0xf bank_mask:0xf
	v_cndmask_b32_e64 v17, v17, v146, s[42:43]
	v_cndmask_b32_e64 v16, v146, v16, s[42:43]
	v_cndmask_b32_e64 v19, v19, v156, s[42:43]
	v_cndmask_b32_e64 v18, v156, v18, s[42:43]
	v_cndmask_b32_e64 v145, v16, v18, s[44:45]
	v_cndmask_b32_e64 v147, v17, v19, s[44:45]
	s_nop 1
	v_mov_b32_dpp v146, v145 quad_perm:[2,3,0,1] row_mask:0xf bank_mask:0xf
	v_mov_b32_dpp v156, v147 quad_perm:[2,3,0,1] row_mask:0xf bank_mask:0xf
	v_cndmask_b32_e64 v18, v18, v146, s[44:45]
	v_cndmask_b32_e64 v16, v146, v16, s[44:45]
	v_cndmask_b32_e64 v19, v19, v156, s[44:45]
	v_cndmask_b32_e64 v17, v156, v17, s[44:45]
	v_cndmask_b32_e64 v145, v20, v21, s[42:43]
	v_cndmask_b32_e64 v147, v22, v23, s[42:43]
	s_nop 1
	v_mov_b32_dpp v146, v145 quad_perm:[1,0,3,2] row_mask:0xf bank_mask:0xf
	v_mov_b32_dpp v156, v147 quad_perm:[1,0,3,2] row_mask:0xf bank_mask:0xf
	v_cndmask_b32_e64 v21, v21, v146, s[42:43]
	v_cndmask_b32_e64 v20, v146, v20, s[42:43]
	v_cndmask_b32_e64 v23, v23, v156, s[42:43]
	v_cndmask_b32_e64 v22, v156, v22, s[42:43]
	v_cndmask_b32_e64 v145, v20, v22, s[44:45]
	v_cndmask_b32_e64 v147, v21, v23, s[44:45]
	s_nop 1
	v_mov_b32_dpp v146, v145 quad_perm:[2,3,0,1] row_mask:0xf bank_mask:0xf
	v_mov_b32_dpp v156, v147 quad_perm:[2,3,0,1] row_mask:0xf bank_mask:0xf
	v_cndmask_b32_e64 v22, v22, v146, s[44:45]
	v_cndmask_b32_e64 v20, v146, v20, s[44:45]
	v_cndmask_b32_e64 v23, v23, v156, s[44:45]
	v_cndmask_b32_e64 v21, v156, v21, s[44:45]
	v_cndmask_b32_e64 v145, v24, v25, s[42:43]
	v_cndmask_b32_e64 v147, v26, v27, s[42:43]
	s_nop 1
	v_mov_b32_dpp v146, v145 quad_perm:[1,0,3,2] row_mask:0xf bank_mask:0xf
	v_mov_b32_dpp v156, v147 quad_perm:[1,0,3,2] row_mask:0xf bank_mask:0xf
	v_cndmask_b32_e64 v25, v25, v146, s[42:43]
	v_cndmask_b32_e64 v24, v146, v24, s[42:43]
	v_cndmask_b32_e64 v27, v27, v156, s[42:43]
	v_cndmask_b32_e64 v26, v156, v26, s[42:43]
	v_cndmask_b32_e64 v145, v24, v26, s[44:45]
	v_cndmask_b32_e64 v147, v25, v27, s[44:45]
	s_nop 1
	v_mov_b32_dpp v146, v145 quad_perm:[2,3,0,1] row_mask:0xf bank_mask:0xf
	v_mov_b32_dpp v156, v147 quad_perm:[2,3,0,1] row_mask:0xf bank_mask:0xf
	v_cndmask_b32_e64 v26, v26, v146, s[44:45]
	v_cndmask_b32_e64 v24, v146, v24, s[44:45]
	v_cndmask_b32_e64 v27, v27, v156, s[44:45]
	v_cndmask_b32_e64 v25, v156, v25, s[44:45]
	v_cndmask_b32_e64 v145, v28, v29, s[42:43]
	v_cndmask_b32_e64 v147, v30, v31, s[42:43]
	s_nop 1
	v_mov_b32_dpp v146, v145 quad_perm:[1,0,3,2] row_mask:0xf bank_mask:0xf
	v_mov_b32_dpp v156, v147 quad_perm:[1,0,3,2] row_mask:0xf bank_mask:0xf
	v_cndmask_b32_e64 v29, v29, v146, s[42:43]
	v_cndmask_b32_e64 v28, v146, v28, s[42:43]
	v_cndmask_b32_e64 v31, v31, v156, s[42:43]
	v_cndmask_b32_e64 v30, v156, v30, s[42:43]
	v_cndmask_b32_e64 v145, v28, v30, s[44:45]
	v_cndmask_b32_e64 v147, v29, v31, s[44:45]
	s_nop 1
	v_mov_b32_dpp v146, v145 quad_perm:[2,3,0,1] row_mask:0xf bank_mask:0xf
	v_mov_b32_dpp v156, v147 quad_perm:[2,3,0,1] row_mask:0xf bank_mask:0xf
	v_cndmask_b32_e64 v30, v30, v146, s[44:45]
	v_cndmask_b32_e64 v28, v146, v28, s[44:45]
	v_cndmask_b32_e64 v31, v31, v156, s[44:45]
	v_cndmask_b32_e64 v29, v156, v29, s[44:45]
	v_cndmask_b32_e64 v145, v32, v33, s[42:43]
	v_cndmask_b32_e64 v147, v34, v35, s[42:43]
	s_nop 1
	v_mov_b32_dpp v146, v145 quad_perm:[1,0,3,2] row_mask:0xf bank_mask:0xf
	v_mov_b32_dpp v156, v147 quad_perm:[1,0,3,2] row_mask:0xf bank_mask:0xf
	v_cndmask_b32_e64 v33, v33, v146, s[42:43]
	v_cndmask_b32_e64 v32, v146, v32, s[42:43]
	v_cndmask_b32_e64 v35, v35, v156, s[42:43]
	v_cndmask_b32_e64 v34, v156, v34, s[42:43]
	v_cndmask_b32_e64 v145, v32, v34, s[44:45]
	v_cndmask_b32_e64 v147, v33, v35, s[44:45]
	s_nop 1
	v_mov_b32_dpp v146, v145 quad_perm:[2,3,0,1] row_mask:0xf bank_mask:0xf
	v_mov_b32_dpp v156, v147 quad_perm:[2,3,0,1] row_mask:0xf bank_mask:0xf
	v_cndmask_b32_e64 v34, v34, v146, s[44:45]
	v_cndmask_b32_e64 v32, v146, v32, s[44:45]
	v_cndmask_b32_e64 v35, v35, v156, s[44:45]
	v_cndmask_b32_e64 v33, v156, v33, s[44:45]
	v_add_u32_e32 v1, 0xd800, v142
	v_add_u32_e32 v2, 0xd800, v143
	v_add_u32_e32 v3, 0xd800, v144
	ds_read_b128 v[164:167], v3 offset:26624
	ds_read_b128 v[168:171], v3 offset:26688
	ds_read_b128 v[172:175], v3 offset:26752
	ds_read_b128 v[176:179], v3 offset:26816
	ds_read_b128 v[180:183], v3 offset:26880
	ds_read_b128 v[184:187], v3 offset:26944
	ds_read_b128 v[148:151], v3 offset:27008
	ds_read_b128 v[152:155], v3 offset:27072
	ds_read_b128 v[84:87], v2 offset:16384
	ds_read_b128 v[88:91], v1 offset:24576
	ds_read_b128 v[92:95], v1 offset:0
	ds_read_b128 v[96:99], v1 offset:1024
	ds_read_b128 v[100:103], v1 offset:2048
	ds_read_b128 v[104:107], v1 offset:3072
	v_cvt_pk_bf16_f32 v68, v4, v5
	v_cvt_pk_bf16_f32 v69, v6, v7
	v_cvt_pk_bf16_f32 v70, v8, v9
	v_cvt_pk_bf16_f32 v71, v10, v11
	v_cvt_pk_bf16_f32 v72, v12, v13
	v_cvt_pk_bf16_f32 v73, v14, v15
	v_cvt_pk_bf16_f32 v74, v16, v17
	v_cvt_pk_bf16_f32 v75, v18, v19
	v_cvt_pk_bf16_f32 v76, v20, v21
	v_cvt_pk_bf16_f32 v77, v22, v23
	v_cvt_pk_bf16_f32 v78, v24, v25
	v_cvt_pk_bf16_f32 v79, v26, v27
	v_cvt_pk_bf16_f32 v80, v28, v29
	v_cvt_pk_bf16_f32 v81, v30, v31
	v_cvt_pk_bf16_f32 v82, v32, v33
	v_cvt_pk_bf16_f32 v83, v34, v35
	s_waitcnt lgkmcnt(6)
; #define LAS __attribute__((address_space(3)))
; __device__ __forceinline__ unsigned pk2(float lo, float hi) { const f32x2_t_ v = {lo, hi}; return __builtin_bit_cast(unsigned, __builtin_convertvector(v, bf16x2_t_)); }
; __device__ __forceinline__ void hg_chunk(const LAS unsigned char* sl, f32x4 (&S)[8], float* Orow, int nvalid, int vs, int lane) {
;     const int r = lane & 15, q = lane >> 4;
;     const bf16x8 vfr = *(const LAS bf16x8*)(sl + 16384 + ((vs * 64 + lane) << 4));
;     f32x4 o0 = {0.f, 0.f, 0.f, 0.f}, o1 = {0.f, 0.f, 0.f, 0.f};
;     { const bf16x8 s0 = *(const LAS bf16x8*)(sl + 24576 + (lane << 4)), s1 = *(const LAS bf16x8*)(sl + 24576 + ((64 + lane) << 4));
;       o0 = __builtin_amdgcn_mfma_f32_16x16x32_bf16(s0, vfr, o0, 0, 0, 0); o1 = __builtin_amdgcn_mfma_f32_16x16x32_bf16(s1, vfr, o1, 0, 0, 0); }
; #pragma unroll
;     for (int m = 0; m < 4; ++m) {
;         v4u sw; sw.x = pk2(S[2 * m][0], S[2 * m][1]); sw.y = pk2(S[2 * m][2], S[2 * m][3]); sw.z = pk2(S[2 * m + 1][0], S[2 * m + 1][1]); sw.w = pk2(S[2 * m + 1][2], S[2 * m + 1][3]);
;         const bf16x8 sb = __builtin_bit_cast(bf16x8, sw);
;         const bf16x8 a0 = *(const LAS bf16x8*)(sl + ((m * 64 + lane) << 4)), a1 = *(const LAS bf16x8*)(sl + (((4 + m) * 64 + lane) << 4));
;         o0 = __builtin_amdgcn_mfma_f32_16x16x32_bf16(a0, sb, o0, 0, 0, 0); o1 = __builtin_amdgcn_mfma_f32_16x16x32_bf16(a1, sb, o1, 0, 0, 0);
;     }
; #pragma unroll
;     for (int i = 0; i < 4; ++i) { const int c0 = 4 * q + i;
;         if (c0 < nvalid) Orow[(size_t)c0 * DA + 16 * vs + r] = o0[i];
;         if (c0 + 16 < nvalid) Orow[(size_t)(c0 + 16) * DA + 16 * vs + r] = o1[i]; }
; #pragma unroll
;     for (int kb = 0; kb < 8; ++kb) { const f32x4 d = *(const LAS f32x4*)(sl + 26624 + ((16 * kb + 4 * q) << 2));
;         const bf16x8 ke = *(const LAS bf16x8*)(sl + 8192 + ((kb * 64 + lane) << 4));
;         S[kb] = __builtin_amdgcn_mfma_f32_16x16x32_bf16(ke, vfr, S[kb] * d, 0, 0, 0); }
	v_pk_mul_f32 v[4:5], v[4:5], v[164:165]
	v_pk_mul_f32 v[6:7], v[6:7], v[166:167]
	v_pk_mul_f32 v[8:9], v[8:9], v[168:169]
	v_pk_mul_f32 v[10:11], v[10:11], v[170:171]
	v_pk_mul_f32 v[12:13], v[12:13], v[172:173]
	v_pk_mul_f32 v[14:15], v[14:15], v[174:175]
	v_pk_mul_f32 v[16:17], v[16:17], v[176:177]
	v_pk_mul_f32 v[18:19], v[18:19], v[178:179]
	v_pk_mul_f32 v[20:21], v[20:21], v[180:181]
	v_pk_mul_f32 v[22:23], v[22:23], v[182:183]
	v_pk_mul_f32 v[24:25], v[24:25], v[184:185]
	v_pk_mul_f32 v[26:27], v[26:27], v[186:187]
	v_pk_mul_f32 v[28:29], v[28:29], v[148:149]
	v_pk_mul_f32 v[30:31], v[30:31], v[150:151]
	v_pk_mul_f32 v[32:33], v[32:33], v[152:153]
	v_pk_mul_f32 v[34:35], v[34:35], v[154:155]
	ds_read_b128 v[108:111], v1 offset:8192
	ds_read_b128 v[112:115], v1 offset:9216
	ds_read_b128 v[116:119], v1 offset:10240
	ds_read_b128 v[120:123], v1 offset:11264
	ds_read_b128 v[124:127], v1 offset:12288
	ds_read_b128 v[128:131], v1 offset:13312
	ds_read_b128 v[132:135], v1 offset:14336
	ds_read_b128 v[136:139], v1 offset:15360
	s_waitcnt lgkmcnt(12)
	v_mfma_f32_16x16x32_bf16 v[196:199], v[88:91], v[84:87], 0
	s_waitcnt lgkmcnt(11)
	v_mfma_f32_16x16x32_bf16 v[196:199], v[92:95], v[68:71], v[196:199]
	s_waitcnt lgkmcnt(10)
	v_mfma_f32_16x16x32_bf16 v[196:199], v[96:99], v[72:75], v[196:199]
	s_waitcnt lgkmcnt(9)
	v_mfma_f32_16x16x32_bf16 v[196:199], v[100:103], v[76:79], v[196:199]
	s_waitcnt lgkmcnt(8)
	v_mfma_f32_16x16x32_bf16 v[196:199], v[104:107], v[80:83], v[196:199]
	s_waitcnt lgkmcnt(7)
	v_mfma_f32_16x16x32_bf16 v[4:7], v[108:111], v[84:87], v[4:7]
	s_waitcnt lgkmcnt(6)
	v_mfma_f32_16x16x32_bf16 v[8:11], v[112:115], v[84:87], v[8:11]
	s_waitcnt lgkmcnt(5)
	v_mfma_f32_16x16x32_bf16 v[12:15], v[116:119], v[84:87], v[12:15]
	s_waitcnt lgkmcnt(4)
	v_mfma_f32_16x16x32_bf16 v[16:19], v[120:123], v[84:87], v[16:19]
	s_waitcnt lgkmcnt(3)
	v_mfma_f32_16x16x32_bf16 v[20:23], v[124:127], v[84:87], v[20:23]
	s_waitcnt lgkmcnt(2)
	v_mfma_f32_16x16x32_bf16 v[24:27], v[128:131], v[84:87], v[24:27]
	s_waitcnt lgkmcnt(1)
	v_mfma_f32_16x16x32_bf16 v[28:31], v[132:135], v[84:87], v[28:31]
	s_waitcnt lgkmcnt(0)
	v_mfma_f32_16x16x32_bf16 v[32:35], v[136:139], v[84:87], v[32:35]
	s_mov_b32 exec_hi, 0
	global_store_dword v208, v196, s[12:13]
	global_store_dword v208, v197, s[12:13] offset:2048
	global_store_dword v209, v198, s[12:13]
	global_store_dword v209, v199, s[12:13] offset:2048
	s_mov_b64 exec, -1
	s_add_u32 s12, s12, 0x80000
	s_addc_u32 s13, s13, 0
	s_nop 7
	v_cndmask_b32_e64 v145, v4, v5, s[42:43]
	v_cndmask_b32_e64 v147, v6, v7, s[42:43]
	s_nop 1
	v_mov_b32_dpp v146, v145 quad_perm:[1,0,3,2] row_mask:0xf bank_mask:0xf
	v_mov_b32_dpp v156, v147 quad_perm:[1,0,3,2] row_mask:0xf bank_mask:0xf
	v_cndmask_b32_e64 v5, v5, v146, s[42:43]
	v_cndmask_b32_e64 v4, v146, v4, s[42:43]
	v_cndmask_b32_e64 v7, v7, v156, s[42:43]
	v_cndmask_b32_e64 v6, v156, v6, s[42:43]
	v_cndmask_b32_e64 v145, v4, v6, s[44:45]
	v_cndmask_b32_e64 v147, v5, v7, s[44:45]
	s_nop 1
	v_mov_b32_dpp v146, v145 quad_perm:[2,3,0,1] row_mask:0xf bank_mask:0xf
	v_mov_b32_dpp v156, v147 quad_perm:[2,3,0,1] row_mask:0xf bank_mask:0xf
	v_cndmask_b32_e64 v6, v6, v146, s[44:45]
	v_cndmask_b32_e64 v4, v146, v4, s[44:45]
	v_cndmask_b32_e64 v7, v7, v156, s[44:45]
	v_cndmask_b32_e64 v5, v156, v5, s[44:45]
	v_cndmask_b32_e64 v145, v8, v9, s[42:43]
	v_cndmask_b32_e64 v147, v10, v11, s[42:43]
	s_nop 1
	v_mov_b32_dpp v146, v145 quad_perm:[1,0,3,2] row_mask:0xf bank_mask:0xf
	v_mov_b32_dpp v156, v147 quad_perm:[1,0,3,2] row_mask:0xf bank_mask:0xf
	v_cndmask_b32_e64 v9, v9, v146, s[42:43]
	v_cndmask_b32_e64 v8, v146, v8, s[42:43]
	v_cndmask_b32_e64 v11, v11, v156, s[42:43]
	v_cndmask_b32_e64 v10, v156, v10, s[42:43]
	v_cndmask_b32_e64 v145, v8, v10, s[44:45]
	v_cndmask_b32_e64 v147, v9, v11, s[44:45]
	s_nop 1
	v_mov_b32_dpp v146, v145 quad_perm:[2,3,0,1] row_mask:0xf bank_mask:0xf
	v_mov_b32_dpp v156, v147 quad_perm:[2,3,0,1] row_mask:0xf bank_mask:0xf
	v_cndmask_b32_e64 v10, v10, v146, s[44:45]
	v_cndmask_b32_e64 v8, v146, v8, s[44:45]
	v_cndmask_b32_e64 v11, v11, v156, s[44:45]
	v_cndmask_b32_e64 v9, v156, v9, s[44:45]
	v_cndmask_b32_e64 v145, v12, v13, s[42:43]
	v_cndmask_b32_e64 v147, v14, v15, s[42:43]
	s_nop 1
	v_mov_b32_dpp v146, v145 quad_perm:[1,0,3,2] row_mask:0xf bank_mask:0xf
	v_mov_b32_dpp v156, v147 quad_perm:[1,0,3,2] row_mask:0xf bank_mask:0xf
	v_cndmask_b32_e64 v13, v13, v146, s[42:43]
	v_cndmask_b32_e64 v12, v146, v12, s[42:43]
	v_cndmask_b32_e64 v15, v15, v156, s[42:43]
	v_cndmask_b32_e64 v14, v156, v14, s[42:43]
	v_cndmask_b32_e64 v145, v12, v14, s[44:45]
	v_cndmask_b32_e64 v147, v13, v15, s[44:45]
	s_nop 1
	v_mov_b32_dpp v146, v145 quad_perm:[2,3,0,1] row_mask:0xf bank_mask:0xf
	v_mov_b32_dpp v156, v147 quad_perm:[2,3,0,1] row_mask:0xf bank_mask:0xf
	v_cndmask_b32_e64 v14, v14, v146, s[44:45]
	v_cndmask_b32_e64 v12, v146, v12, s[44:45]
	v_cndmask_b32_e64 v15, v15, v156, s[44:45]
	v_cndmask_b32_e64 v13, v156, v13, s[44:45]
	v_cndmask_b32_e64 v145, v16, v17, s[42:43]
	v_cndmask_b32_e64 v147, v18, v19, s[42:43]
	s_nop 1
	v_mov_b32_dpp v146, v145 quad_perm:[1,0,3,2] row_mask:0xf bank_mask:0xf
	v_mov_b32_dpp v156, v147 quad_perm:[1,0,3,2] row_mask:0xf bank_mask:0xf
	v_cndmask_b32_e64 v17, v17, v146, s[42:43]
	v_cndmask_b32_e64 v16, v146, v16, s[42:43]
	v_cndmask_b32_e64 v19, v19, v156, s[42:43]
	v_cndmask_b32_e64 v18, v156, v18, s[42:43]
	v_cndmask_b32_e64 v145, v16, v18, s[44:45]
; __device__ __forceinline__ const float* kin(int k) { KArgs p = (KArgs)__builtin_amdgcn_kernarg_segment_ptr(); asm volatile("" : "+s"(p)); return p->in[k]; }
; __device__ __forceinline__ void hg_seq(const Frame& F, unsigned char* ws, const float* s0, float* sout, float* Og, int seq, bool sample, int vs_base, int nvs) {
;     ...
;     if (active) {
; #pragma unroll
;     for (int kb = 0; kb < 8; ++kb)
; #pragma unroll
;         for (int i = 0; i < 4; ++i) sout[((size_t)seq * 128 + 16 * kb + 4 * q + i) * 128 + 16 * vs + r] = S[kb][i];
;     }
; __global__ void __launch_bounds__(NWAVES * 64, 2) mk_fwd(Args args) {
;     ...
;                 const int cgw = (bid - NSCAN) * NWAVES + F.wave, CNGW = (G - NSCAN) * NWAVES;
;                 zb_rows(ws, kin(11), st_c, out, F.lane, cgw, CNGW);
;                 conv_mat(kin(13), nullptr, DM, DA, DM, (bf16*)(ws + WS_WA), 0, 0, SCR_, F.lane, cgw, CNGW);
;                 conv_mat(kin(14), nullptr, DM, DA, DM, (bf16*)(ws + WS_WB), 0, 0, SCR_, F.lane, (cgw + CNGW / 4) % CNGW, CNGW);
;                 conv_mat(kin(15), nullptr, DM, DM, DM, (bf16*)(ws + WS_WO), 0, 0, SCR_, F.lane, (cgw + CNGW / 2) % CNGW, CNGW);
	v_cndmask_b32_e64 v147, v17, v19, s[44:45]
	s_nop 1
	v_mov_b32_dpp v146, v145 quad_perm:[2,3,0,1] row_mask:0xf bank_mask:0xf
	v_mov_b32_dpp v156, v147 quad_perm:[2,3,0,1] row_mask:0xf bank_mask:0xf
	v_cndmask_b32_e64 v18, v18, v146, s[44:45]
	v_cndmask_b32_e64 v16, v146, v16, s[44:45]
	v_cndmask_b32_e64 v19, v19, v156, s[44:45]
	v_cndmask_b32_e64 v17, v156, v17, s[44:45]
	v_cndmask_b32_e64 v145, v20, v21, s[42:43]
	v_cndmask_b32_e64 v147, v22, v23, s[42:43]
	s_nop 1
	v_mov_b32_dpp v146, v145 quad_perm:[1,0,3,2] row_mask:0xf bank_mask:0xf
	v_mov_b32_dpp v156, v147 quad_perm:[1,0,3,2] row_mask:0xf bank_mask:0xf
	v_cndmask_b32_e64 v21, v21, v146, s[42:43]
	v_cndmask_b32_e64 v20, v146, v20, s[42:43]
	v_cndmask_b32_e64 v23, v23, v156, s[42:43]
	v_cndmask_b32_e64 v22, v156, v22, s[42:43]
	v_cndmask_b32_e64 v145, v20, v22, s[44:45]
	v_cndmask_b32_e64 v147, v21, v23, s[44:45]
	s_nop 1
	v_mov_b32_dpp v146, v145 quad_perm:[2,3,0,1] row_mask:0xf bank_mask:0xf
	v_mov_b32_dpp v156, v147 quad_perm:[2,3,0,1] row_mask:0xf bank_mask:0xf
	v_cndmask_b32_e64 v22, v22, v146, s[44:45]
	v_cndmask_b32_e64 v20, v146, v20, s[44:45]
	v_cndmask_b32_e64 v23, v23, v156, s[44:45]
	v_cndmask_b32_e64 v21, v156, v21, s[44:45]
	v_cndmask_b32_e64 v145, v24, v25, s[42:43]
	v_cndmask_b32_e64 v147, v26, v27, s[42:43]
	s_nop 1
	v_mov_b32_dpp v146, v145 quad_perm:[1,0,3,2] row_mask:0xf bank_mask:0xf
	v_mov_b32_dpp v156, v147 quad_perm:[1,0,3,2] row_mask:0xf bank_mask:0xf
	v_cndmask_b32_e64 v25, v25, v146, s[42:43]
	v_cndmask_b32_e64 v24, v146, v24, s[42:43]
	v_cndmask_b32_e64 v27, v27, v156, s[42:43]
	v_cndmask_b32_e64 v26, v156, v26, s[42:43]
	v_cndmask_b32_e64 v145, v24, v26, s[44:45]
	v_cndmask_b32_e64 v147, v25, v27, s[44:45]
	s_nop 1
	v_mov_b32_dpp v146, v145 quad_perm:[2,3,0,1] row_mask:0xf bank_mask:0xf
	v_mov_b32_dpp v156, v147 quad_perm:[2,3,0,1] row_mask:0xf bank_mask:0xf
	v_cndmask_b32_e64 v26, v26, v146, s[44:45]
	v_cndmask_b32_e64 v24, v146, v24, s[44:45]
	v_cndmask_b32_e64 v27, v27, v156, s[44:45]
	v_cndmask_b32_e64 v25, v156, v25, s[44:45]
	v_cndmask_b32_e64 v145, v28, v29, s[42:43]
	v_cndmask_b32_e64 v147, v30, v31, s[42:43]
	s_nop 1
	v_mov_b32_dpp v146, v145 quad_perm:[1,0,3,2] row_mask:0xf bank_mask:0xf
	v_mov_b32_dpp v156, v147 quad_perm:[1,0,3,2] row_mask:0xf bank_mask:0xf
	v_cndmask_b32_e64 v29, v29, v146, s[42:43]
	v_cndmask_b32_e64 v28, v146, v28, s[42:43]
	v_cndmask_b32_e64 v31, v31, v156, s[42:43]
	v_cndmask_b32_e64 v30, v156, v30, s[42:43]
	v_cndmask_b32_e64 v145, v28, v30, s[44:45]
	v_cndmask_b32_e64 v147, v29, v31, s[44:45]
	s_nop 1
	v_mov_b32_dpp v146, v145 quad_perm:[2,3,0,1] row_mask:0xf bank_mask:0xf
	v_mov_b32_dpp v156, v147 quad_perm:[2,3,0,1] row_mask:0xf bank_mask:0xf
	v_cndmask_b32_e64 v30, v30, v146, s[44:45]
	v_cndmask_b32_e64 v28, v146, v28, s[44:45]
	v_cndmask_b32_e64 v31, v31, v156, s[44:45]
	v_cndmask_b32_e64 v29, v156, v29, s[44:45]
	v_cndmask_b32_e64 v145, v32, v33, s[42:43]
	v_cndmask_b32_e64 v147, v34, v35, s[42:43]
	s_nop 1
	v_mov_b32_dpp v146, v145 quad_perm:[1,0,3,2] row_mask:0xf bank_mask:0xf
	v_mov_b32_dpp v156, v147 quad_perm:[1,0,3,2] row_mask:0xf bank_mask:0xf
	v_cndmask_b32_e64 v33, v33, v146, s[42:43]
	v_cndmask_b32_e64 v32, v146, v32, s[42:43]
	v_cndmask_b32_e64 v35, v35, v156, s[42:43]
	v_cndmask_b32_e64 v34, v156, v34, s[42:43]
	v_cndmask_b32_e64 v145, v32, v34, s[44:45]
	v_cndmask_b32_e64 v147, v33, v35, s[44:45]
	s_nop 1
	v_mov_b32_dpp v146, v145 quad_perm:[2,3,0,1] row_mask:0xf bank_mask:0xf
	v_mov_b32_dpp v156, v147 quad_perm:[2,3,0,1] row_mask:0xf bank_mask:0xf
	v_cndmask_b32_e64 v34, v34, v146, s[44:45]
	v_cndmask_b32_e64 v32, v146, v32, s[44:45]
	v_cndmask_b32_e64 v35, v35, v156, s[44:45]
	v_cndmask_b32_e64 v33, v156, v33, s[44:45]
	global_store_dwordx4 v200, v[4:7], s[10:11]
	global_store_dwordx4 v201, v[8:11], s[10:11]
	global_store_dwordx4 v202, v[12:15], s[10:11]
	global_store_dwordx4 v203, v[16:19], s[10:11]
	global_store_dwordx4 v204, v[20:23], s[10:11]
	global_store_dwordx4 v205, v[24:27], s[10:11]
	global_store_dwordx4 v206, v[28:31], s[10:11]
	global_store_dwordx4 v207, v[32:35], s[10:11]
	s_add_u32 s10, s10, s34
	s_addc_u32 s11, s11, 0
	s_waitcnt lgkmcnt(0)
	s_barrier
	s_mov_b64 exec, -1
	v_readfirstlane_b32 s3, v0
	s_lshr_b32 s3, s3, 6
	s_lshl_b32 s12, s3, 14
	s_sub_i32 s10, s2, 0x80
	s_lshl_b32 s10, s10, 3
	s_add_i32 s10, s10, s3
	s_sub_i32 s11, s18, 0x80
	s_lshl_b32 s11, s11, 3
	v_and_b32_e32 v15, 63, v0
	v_lshrrev_b32_e32 v2, 3, v15
	v_and_b32_e32 v3, 7, v15
	v_lshlrev_b32_e32 v3, 4, v3
	v_mul_u32_u24_e32 v4, 0x84, v2
	v_add3_u32 v4, v4, v3, s12
	v_and_b32_e32 v5, 7, v15
	v_mul_u32_u24_e32 v5, 0x420, v5
	v_lshl_add_u32 v5, v2, 2, v5
	v_add_u32_e32 v5, s12, v5
	v_add_u32_e32 v6, 0, v2
	v_lshrrev_b32_e32 v10, 4, v6
	v_lshlrev_b32_e32 v10, 5, v10
	v_and_b32_e32 v14, 15, v6
	v_or_b32_e32 v10, v10, v14
	v_add_u32_e32 v7, 8, v2
	v_lshrrev_b32_e32 v11, 4, v7
	v_lshlrev_b32_e32 v11, 5, v11
	v_and_b32_e32 v14, 15, v7
	v_or_b32_e32 v11, v11, v14
	v_add_u32_e32 v8, 16, v2
	v_lshrrev_b32_e32 v12, 4, v8
	v_lshlrev_b32_e32 v12, 5, v12
	v_and_b32_e32 v14, 15, v8
	v_or_b32_e32 v12, v12, v14
	v_add_u32_e32 v9, 24, v2
	v_lshrrev_b32_e32 v13, 4, v9
	v_lshlrev_b32_e32 v13, 5, v13
	v_and_b32_e32 v14, 15, v9
	v_or_b32_e32 v13, v13, v14
	s_cmp_lt_u32 s10, 1024
	s_cbranch_scc0 .Lcw_p4b_done
	s_cmp_lt_u32 s10, 256
	s_cbranch_scc1 .Lcw_p4b_i0_c0
	s_cmp_lt_u32 s10, 512
	s_cbranch_scc1 .Lcw_p4b_i0_c1
